# hdn0 hand-written (fragment-major bf16 layout) + inproj0 loop with A fragments loaded directly (coalesced) and B via 4-stage LDS ring
# baseline (speedup 1.0000x reference)
.LBB0_111:
	s_or_b64 exec, exec, s[0:1]
	s_cmpk_lt_i32 s2, 0x200
	s_cselect_b64 s[26:27], -1, 0
	s_cmpk_gt_i32 s2, 0x1ff
	v_lshrrev_b32_e32 v157, 3, v131
	v_mbcnt_lo_u32_b32 v155, -1, 0
	s_waitcnt lgkmcnt(0)
	s_barrier
	s_cbranch_scc1 .LBB0_116
	s_mov_b32 s4, s2
.Lmy_hdn0_loop:
	s_lshr_b32 s5, s4, 7
	s_mul_i32 s5, s5, 0x3000
	s_add_u32 s6, s50, s5
	s_addc_u32 s7, s51, 0
	s_add_u32 s6, s6, 0x10c0000
	s_addc_u32 s7, s7, 0
	v_add_u32_e32 v210, 0x1000, v129
	s_barrier
	global_load_dwordx4 v[0:3], v129, s[6:7]
	global_load_dwordx4 v[32:35], v210, s[6:7]
	s_add_u32 s6, s6, 0xc000
	s_addc_u32 s7, s7, 0
	global_load_dwordx4 v[4:7], v129, s[6:7]
	global_load_dwordx4 v[36:39], v210, s[6:7]
	s_add_u32 s6, s6, 0xc000
	s_addc_u32 s7, s7, 0
	global_load_dwordx4 v[8:11], v129, s[6:7]
	global_load_dwordx4 v[40:43], v210, s[6:7]
	s_add_u32 s6, s6, 0xc000
	s_addc_u32 s7, s7, 0
	global_load_dwordx4 v[12:15], v129, s[6:7]
	global_load_dwordx4 v[44:47], v210, s[6:7]
	s_add_u32 s6, s6, 0xc000
	s_addc_u32 s7, s7, 0
	global_load_dwordx4 v[16:19], v129, s[6:7]
	global_load_dwordx4 v[48:51], v210, s[6:7]
	s_add_u32 s6, s6, 0xc000
	s_addc_u32 s7, s7, 0
	global_load_dwordx4 v[20:23], v129, s[6:7]
	global_load_dwordx4 v[52:55], v210, s[6:7]
	s_add_u32 s6, s6, 0xc000
	s_addc_u32 s7, s7, 0
	global_load_dwordx4 v[24:27], v129, s[6:7]
	global_load_dwordx4 v[56:59], v210, s[6:7]
	s_add_u32 s6, s6, 0xc000
	s_addc_u32 s7, s7, 0
	global_load_dwordx4 v[28:31], v129, s[6:7]
	global_load_dwordx4 v[60:63], v210, s[6:7]
	global_load_dwordx4 v[64:67], v129, s[74:75]
	v_and_b32_e32 v173, 63, v131
	v_lshrrev_b32_e32 v172, 6, v131
	v_lshlrev_b32_e32 v168, 4, v173
	v_lshl_add_u32 v168, v172, 15, v168
	v_lshrrev_b32_e32 v169, 3, v173
	v_lshlrev_b32_e32 v169, 10, v169
	v_bfe_u32 v170, v173, 1, 2
	v_lshl_or_b32 v169, v170, 8, v169
	v_and_b32_e32 v170, 1, v173
	v_lshl_or_b32 v169, v170, 3, v169
	v_lshrrev_b32_e32 v170, 1, v172
	v_lshl_or_b32 v169, v170, 15, v169
	v_and_b32_e32 v170, 1, v172
	v_lshl_or_b32 v169, v170, 7, v169
	v_add_u32_e32 v170, 0x2000, v169
	v_add_u32_e32 v171, 0x4000, v169
	v_add_u32_e32 v172, 0x6000, v169
	v_lshlrev_b32_e32 v173, 4, v173
	v_mov_b32_e32 v174, 0x3a800000
	s_lshl_b32 s5, s4, 17
	s_add_u32 s8, s68, s5
	s_addc_u32 s9, s69, 0
	s_lshl_b32 s5, s4, 16
	s_add_u32 s10, s50, s5
	s_addc_u32 s11, s51, 0
	s_add_u32 s10, s10, 0x3a00000
	s_addc_u32 s11, s11, 0
	s_waitcnt vmcnt(0)
	v_add_f32_e32 v0, v0, v4
	v_add_f32_e32 v0, v0, v8
	v_add_f32_e32 v0, v0, v12
	v_add_f32_e32 v0, v0, v16
	v_add_f32_e32 v0, v0, v20
	v_add_f32_e32 v0, v0, v24
	v_add_f32_e32 v0, v0, v28
	v_add_f32_e32 v1, v1, v5
	v_add_f32_e32 v1, v1, v9
	v_add_f32_e32 v1, v1, v13
	v_add_f32_e32 v1, v1, v17
	v_add_f32_e32 v1, v1, v21
	v_add_f32_e32 v1, v1, v25
	v_add_f32_e32 v1, v1, v29
	v_add_f32_e32 v2, v2, v6
	v_add_f32_e32 v2, v2, v10
	v_add_f32_e32 v2, v2, v14
	v_add_f32_e32 v2, v2, v18
	v_add_f32_e32 v2, v2, v22
	v_add_f32_e32 v2, v2, v26
	v_add_f32_e32 v2, v2, v30
	v_add_f32_e32 v3, v3, v7
	v_add_f32_e32 v3, v3, v11
	v_add_f32_e32 v3, v3, v15
	v_add_f32_e32 v3, v3, v19
	v_add_f32_e32 v3, v3, v23
	v_add_f32_e32 v3, v3, v27
	v_add_f32_e32 v3, v3, v31
	v_add_f32_e32 v32, v32, v36
	v_add_f32_e32 v32, v32, v40
	v_add_f32_e32 v32, v32, v44
	v_add_f32_e32 v32, v32, v48
	v_add_f32_e32 v32, v32, v52
	v_add_f32_e32 v32, v32, v56
	v_add_f32_e32 v32, v32, v60
	v_add_f32_e32 v33, v33, v37
	v_add_f32_e32 v33, v33, v41
	v_add_f32_e32 v33, v33, v45
	v_add_f32_e32 v33, v33, v49
	v_add_f32_e32 v33, v33, v53
	v_add_f32_e32 v33, v33, v57
	v_add_f32_e32 v33, v33, v61
	v_add_f32_e32 v34, v34, v38
	v_add_f32_e32 v34, v34, v42
	v_add_f32_e32 v34, v34, v46
	v_add_f32_e32 v34, v34, v50
	v_add_f32_e32 v34, v34, v54
	v_add_f32_e32 v34, v34, v58
	v_add_f32_e32 v34, v34, v62
	v_add_f32_e32 v35, v35, v39
	v_add_f32_e32 v35, v35, v43
	v_add_f32_e32 v35, v35, v47
	v_add_f32_e32 v35, v35, v51
	v_add_f32_e32 v35, v35, v55
	v_add_f32_e32 v35, v35, v59
	v_add_f32_e32 v35, v35, v63
	v_add_f32_e32 v32, 1.0, v32
	v_add_f32_e32 v33, 1.0, v33
	v_add_f32_e32 v34, 1.0, v34
	v_add_f32_e32 v35, 1.0, v35
	v_mul_f32_e32 v200, v64, v32
	v_mul_f32_e32 v201, v65, v33
	v_mul_f32_e32 v202, v66, v34
	v_mul_f32_e32 v203, v67, v35
	v_mov_b32_e32 v204, v0
	v_mov_b32_e32 v205, v1
	v_mov_b32_e32 v206, v2
	v_mov_b32_e32 v207, v3
	ds_write_b128 v129, v[200:203]
	ds_write_b128 v129, v[204:207] offset:4096
	global_load_dwordx4 v[0:3], v168, s[8:9] offset:0 nt
	global_load_dwordx4 v[4:7], v168, s[8:9] offset:1024 nt
	global_load_dwordx4 v[8:11], v168, s[8:9] offset:2048 nt
	global_load_dwordx4 v[12:15], v168, s[8:9] offset:3072 nt
	s_add_u32 s8, s8, 0x1000
	s_addc_u32 s9, s9, 0
	global_load_dwordx4 v[16:19], v168, s[8:9] offset:0 nt
	global_load_dwordx4 v[20:23], v168, s[8:9] offset:1024 nt
	global_load_dwordx4 v[24:27], v168, s[8:9] offset:2048 nt
	global_load_dwordx4 v[28:31], v168, s[8:9] offset:3072 nt
	s_add_u32 s8, s8, 0x1000
	s_addc_u32 s9, s9, 0
	global_load_dwordx4 v[32:35], v168, s[8:9] offset:0 nt
	global_load_dwordx4 v[36:39], v168, s[8:9] offset:1024 nt
	global_load_dwordx4 v[40:43], v168, s[8:9] offset:2048 nt
	global_load_dwordx4 v[44:47], v168, s[8:9] offset:3072 nt
	s_add_u32 s8, s8, 0x1000
	s_addc_u32 s9, s9, 0
	global_load_dwordx4 v[48:51], v168, s[8:9] offset:0 nt
	global_load_dwordx4 v[52:55], v168, s[8:9] offset:1024 nt
	global_load_dwordx4 v[56:59], v168, s[8:9] offset:2048 nt
	global_load_dwordx4 v[60:63], v168, s[8:9] offset:3072 nt
	s_add_u32 s8, s8, 0x1000
	s_addc_u32 s9, s9, 0
	global_load_dwordx4 v[64:67], v168, s[8:9] offset:0 nt
	global_load_dwordx4 v[68:71], v168, s[8:9] offset:1024 nt
	global_load_dwordx4 v[72:75], v168, s[8:9] offset:2048 nt
	global_load_dwordx4 v[76:79], v168, s[8:9] offset:3072 nt
	s_add_u32 s8, s8, 0x1000
	s_addc_u32 s9, s9, 0
	global_load_dwordx4 v[80:83], v168, s[8:9] offset:0 nt
	global_load_dwordx4 v[84:87], v168, s[8:9] offset:1024 nt
	global_load_dwordx4 v[88:91], v168, s[8:9] offset:2048 nt
	global_load_dwordx4 v[92:95], v168, s[8:9] offset:3072 nt
	s_add_u32 s8, s8, 0x1000
	s_addc_u32 s9, s9, 0
	global_load_dwordx4 v[96:99], v168, s[8:9] offset:0 nt
	global_load_dwordx4 v[100:103], v168, s[8:9] offset:1024 nt
	global_load_dwordx4 v[104:107], v168, s[8:9] offset:2048 nt
	global_load_dwordx4 v[108:111], v168, s[8:9] offset:3072 nt
	s_add_u32 s8, s8, 0x1000
	s_addc_u32 s9, s9, 0
	global_load_dwordx4 v[112:115], v168, s[8:9] offset:0 nt
	global_load_dwordx4 v[116:119], v168, s[8:9] offset:1024 nt
	global_load_dwordx4 v[120:123], v168, s[8:9] offset:2048 nt
	global_load_dwordx4 v[124:127], v168, s[8:9] offset:3072 nt
	s_waitcnt lgkmcnt(0)
	s_barrier
	ds_read_b128 v[178:181], v173 offset:0
	ds_read_b128 v[194:197], v173 offset:4096
	ds_read_b128 v[182:185], v173 offset:1024
	ds_read_b128 v[198:201], v173 offset:5120
	ds_read_b128 v[186:189], v173 offset:2048
	ds_read_b128 v[202:205], v173 offset:6144
	ds_read_b128 v[190:193], v173 offset:3072
	ds_read_b128 v[206:209], v173 offset:7168
	s_waitcnt vmcnt(28)
	v_mul_f32_e32 v160, v0, v0
	v_fmac_f32_e32 v160, v1, v1
	v_fmac_f32_e32 v160, v2, v2
	v_fmac_f32_e32 v160, v3, v3
	v_fmac_f32_e32 v160, v4, v4
	v_fmac_f32_e32 v160, v5, v5
	v_fmac_f32_e32 v160, v6, v6
	v_fmac_f32_e32 v160, v7, v7
	v_fmac_f32_e32 v160, v8, v8
	v_fmac_f32_e32 v160, v9, v9
	v_fmac_f32_e32 v160, v10, v10
	v_fmac_f32_e32 v160, v11, v11
	v_fmac_f32_e32 v160, v12, v12
	v_fmac_f32_e32 v160, v13, v13
	v_fmac_f32_e32 v160, v14, v14
	v_fmac_f32_e32 v160, v15, v15
	s_waitcnt vmcnt(24)
	v_mul_f32_e32 v161, v16, v16
	v_fmac_f32_e32 v161, v17, v17
	v_fmac_f32_e32 v161, v18, v18
	v_fmac_f32_e32 v161, v19, v19
	v_fmac_f32_e32 v161, v20, v20
	v_fmac_f32_e32 v161, v21, v21
	v_fmac_f32_e32 v161, v22, v22
	v_fmac_f32_e32 v161, v23, v23
	v_fmac_f32_e32 v161, v24, v24
	v_fmac_f32_e32 v161, v25, v25
	v_fmac_f32_e32 v161, v26, v26
	v_fmac_f32_e32 v161, v27, v27
	v_fmac_f32_e32 v161, v28, v28
	v_fmac_f32_e32 v161, v29, v29
	v_fmac_f32_e32 v161, v30, v30
	v_fmac_f32_e32 v161, v31, v31
	s_waitcnt vmcnt(20)
	v_mul_f32_e32 v162, v32, v32
	v_fmac_f32_e32 v162, v33, v33
	v_fmac_f32_e32 v162, v34, v34
	v_fmac_f32_e32 v162, v35, v35
	v_fmac_f32_e32 v162, v36, v36
	v_fmac_f32_e32 v162, v37, v37
	v_fmac_f32_e32 v162, v38, v38
	v_fmac_f32_e32 v162, v39, v39
	v_fmac_f32_e32 v162, v40, v40
	v_fmac_f32_e32 v162, v41, v41
	v_fmac_f32_e32 v162, v42, v42
	v_fmac_f32_e32 v162, v43, v43
	v_fmac_f32_e32 v162, v44, v44
	v_fmac_f32_e32 v162, v45, v45
	v_fmac_f32_e32 v162, v46, v46
	v_fmac_f32_e32 v162, v47, v47
	s_waitcnt vmcnt(16)
	v_mul_f32_e32 v163, v48, v48
	v_fmac_f32_e32 v163, v49, v49
	v_fmac_f32_e32 v163, v50, v50
	v_fmac_f32_e32 v163, v51, v51
	v_fmac_f32_e32 v163, v52, v52
	v_fmac_f32_e32 v163, v53, v53
	v_fmac_f32_e32 v163, v54, v54
	v_fmac_f32_e32 v163, v55, v55
	v_fmac_f32_e32 v163, v56, v56
	v_fmac_f32_e32 v163, v57, v57
	v_fmac_f32_e32 v163, v58, v58
	v_fmac_f32_e32 v163, v59, v59
	v_fmac_f32_e32 v163, v60, v60
	v_fmac_f32_e32 v163, v61, v61
	v_fmac_f32_e32 v163, v62, v62
	v_fmac_f32_e32 v163, v63, v63
	s_waitcnt vmcnt(12)
	v_mul_f32_e32 v164, v64, v64
	v_fmac_f32_e32 v164, v65, v65
	v_fmac_f32_e32 v164, v66, v66
	v_fmac_f32_e32 v164, v67, v67
	v_fmac_f32_e32 v164, v68, v68
	v_fmac_f32_e32 v164, v69, v69
	v_fmac_f32_e32 v164, v70, v70
	v_fmac_f32_e32 v164, v71, v71
	v_fmac_f32_e32 v164, v72, v72
	v_fmac_f32_e32 v164, v73, v73
	v_fmac_f32_e32 v164, v74, v74
	v_fmac_f32_e32 v164, v75, v75
	v_fmac_f32_e32 v164, v76, v76
	v_fmac_f32_e32 v164, v77, v77
	v_fmac_f32_e32 v164, v78, v78
	v_fmac_f32_e32 v164, v79, v79
	s_waitcnt vmcnt(8)
	v_mul_f32_e32 v165, v80, v80
	v_fmac_f32_e32 v165, v81, v81
	v_fmac_f32_e32 v165, v82, v82
	v_fmac_f32_e32 v165, v83, v83
	v_fmac_f32_e32 v165, v84, v84
	v_fmac_f32_e32 v165, v85, v85
	v_fmac_f32_e32 v165, v86, v86
	v_fmac_f32_e32 v165, v87, v87
	v_fmac_f32_e32 v165, v88, v88
	v_fmac_f32_e32 v165, v89, v89
	v_fmac_f32_e32 v165, v90, v90
	v_fmac_f32_e32 v165, v91, v91
	v_fmac_f32_e32 v165, v92, v92
	v_fmac_f32_e32 v165, v93, v93
	v_fmac_f32_e32 v165, v94, v94
	v_fmac_f32_e32 v165, v95, v95
	s_waitcnt vmcnt(4)
	v_mul_f32_e32 v166, v96, v96
	v_fmac_f32_e32 v166, v97, v97
	v_fmac_f32_e32 v166, v98, v98
	v_fmac_f32_e32 v166, v99, v99
	v_fmac_f32_e32 v166, v100, v100
	v_fmac_f32_e32 v166, v101, v101
	v_fmac_f32_e32 v166, v102, v102
	v_fmac_f32_e32 v166, v103, v103
	v_fmac_f32_e32 v166, v104, v104
	v_fmac_f32_e32 v166, v105, v105
	v_fmac_f32_e32 v166, v106, v106
	v_fmac_f32_e32 v166, v107, v107
	v_fmac_f32_e32 v166, v108, v108
	v_fmac_f32_e32 v166, v109, v109
	v_fmac_f32_e32 v166, v110, v110
	v_fmac_f32_e32 v166, v111, v111
	s_waitcnt vmcnt(0)
	v_mul_f32_e32 v167, v112, v112
	v_fmac_f32_e32 v167, v113, v113
	v_fmac_f32_e32 v167, v114, v114
	v_fmac_f32_e32 v167, v115, v115
	v_fmac_f32_e32 v167, v116, v116
	v_fmac_f32_e32 v167, v117, v117
	v_fmac_f32_e32 v167, v118, v118
	v_fmac_f32_e32 v167, v119, v119
	v_fmac_f32_e32 v167, v120, v120
	v_fmac_f32_e32 v167, v121, v121
	v_fmac_f32_e32 v167, v122, v122
	v_fmac_f32_e32 v167, v123, v123
	v_fmac_f32_e32 v167, v124, v124
	v_fmac_f32_e32 v167, v125, v125
	v_fmac_f32_e32 v167, v126, v126
	v_fmac_f32_e32 v167, v127, v127
	v_add_f32_dpp v160, v160, v160 quad_perm:[1,0,3,2] row_mask:0xf bank_mask:0xf
	v_add_f32_dpp v161, v161, v161 quad_perm:[1,0,3,2] row_mask:0xf bank_mask:0xf
	v_add_f32_dpp v162, v162, v162 quad_perm:[1,0,3,2] row_mask:0xf bank_mask:0xf
	v_add_f32_dpp v163, v163, v163 quad_perm:[1,0,3,2] row_mask:0xf bank_mask:0xf
	v_add_f32_dpp v164, v164, v164 quad_perm:[1,0,3,2] row_mask:0xf bank_mask:0xf
	v_add_f32_dpp v165, v165, v165 quad_perm:[1,0,3,2] row_mask:0xf bank_mask:0xf
	v_add_f32_dpp v166, v166, v166 quad_perm:[1,0,3,2] row_mask:0xf bank_mask:0xf
	v_add_f32_dpp v167, v167, v167 quad_perm:[1,0,3,2] row_mask:0xf bank_mask:0xf
	v_add_f32_dpp v160, v160, v160 quad_perm:[2,3,0,1] row_mask:0xf bank_mask:0xf
	v_add_f32_dpp v161, v161, v161 quad_perm:[2,3,0,1] row_mask:0xf bank_mask:0xf
	v_add_f32_dpp v162, v162, v162 quad_perm:[2,3,0,1] row_mask:0xf bank_mask:0xf
	v_add_f32_dpp v163, v163, v163 quad_perm:[2,3,0,1] row_mask:0xf bank_mask:0xf
	v_add_f32_dpp v164, v164, v164 quad_perm:[2,3,0,1] row_mask:0xf bank_mask:0xf
	v_add_f32_dpp v165, v165, v165 quad_perm:[2,3,0,1] row_mask:0xf bank_mask:0xf
	v_add_f32_dpp v166, v166, v166 quad_perm:[2,3,0,1] row_mask:0xf bank_mask:0xf
	v_add_f32_dpp v167, v167, v167 quad_perm:[2,3,0,1] row_mask:0xf bank_mask:0xf
	v_add_f32_dpp v160, v160, v160 row_half_mirror row_mask:0xf bank_mask:0xf
	v_add_f32_dpp v161, v161, v161 row_half_mirror row_mask:0xf bank_mask:0xf
	v_add_f32_dpp v162, v162, v162 row_half_mirror row_mask:0xf bank_mask:0xf
	v_add_f32_dpp v163, v163, v163 row_half_mirror row_mask:0xf bank_mask:0xf
	v_add_f32_dpp v164, v164, v164 row_half_mirror row_mask:0xf bank_mask:0xf
	v_add_f32_dpp v165, v165, v165 row_half_mirror row_mask:0xf bank_mask:0xf
	v_add_f32_dpp v166, v166, v166 row_half_mirror row_mask:0xf bank_mask:0xf
	v_add_f32_dpp v167, v167, v167 row_half_mirror row_mask:0xf bank_mask:0xf
	v_add_f32_dpp v160, v160, v160 row_mirror row_mask:0xf bank_mask:0xf
	v_add_f32_dpp v161, v161, v161 row_mirror row_mask:0xf bank_mask:0xf
	v_add_f32_dpp v162, v162, v162 row_mirror row_mask:0xf bank_mask:0xf
	v_add_f32_dpp v163, v163, v163 row_mirror row_mask:0xf bank_mask:0xf
	v_add_f32_dpp v164, v164, v164 row_mirror row_mask:0xf bank_mask:0xf
	v_add_f32_dpp v165, v165, v165 row_mirror row_mask:0xf bank_mask:0xf
	v_add_f32_dpp v166, v166, v166 row_mirror row_mask:0xf bank_mask:0xf
	v_add_f32_dpp v167, v167, v167 row_mirror row_mask:0xf bank_mask:0xf
	v_add_f32_dpp v160, v160, v160 row_bcast:15 row_mask:0xa bank_mask:0xf
	v_add_f32_dpp v161, v161, v161 row_bcast:15 row_mask:0xa bank_mask:0xf
	v_add_f32_dpp v162, v162, v162 row_bcast:15 row_mask:0xa bank_mask:0xf
	v_add_f32_dpp v163, v163, v163 row_bcast:15 row_mask:0xa bank_mask:0xf
	v_add_f32_dpp v164, v164, v164 row_bcast:15 row_mask:0xa bank_mask:0xf
	v_add_f32_dpp v165, v165, v165 row_bcast:15 row_mask:0xa bank_mask:0xf
	v_add_f32_dpp v166, v166, v166 row_bcast:15 row_mask:0xa bank_mask:0xf
	v_add_f32_dpp v167, v167, v167 row_bcast:15 row_mask:0xa bank_mask:0xf
	v_add_f32_dpp v160, v160, v160 row_bcast:31 row_mask:0xc bank_mask:0xf
	v_add_f32_dpp v161, v161, v161 row_bcast:31 row_mask:0xc bank_mask:0xf
	v_add_f32_dpp v162, v162, v162 row_bcast:31 row_mask:0xc bank_mask:0xf
	v_add_f32_dpp v163, v163, v163 row_bcast:31 row_mask:0xc bank_mask:0xf
	v_add_f32_dpp v164, v164, v164 row_bcast:31 row_mask:0xc bank_mask:0xf
	v_add_f32_dpp v165, v165, v165 row_bcast:31 row_mask:0xc bank_mask:0xf
	v_add_f32_dpp v166, v166, v166 row_bcast:31 row_mask:0xc bank_mask:0xf
	v_add_f32_dpp v167, v167, v167 row_bcast:31 row_mask:0xc bank_mask:0xf
	v_fmaak_f32 v160, v160, v174, 0x358637bd
	v_fmaak_f32 v161, v161, v174, 0x358637bd
	v_fmaak_f32 v162, v162, v174, 0x358637bd
	v_fmaak_f32 v163, v163, v174, 0x358637bd
	v_fmaak_f32 v164, v164, v174, 0x358637bd
	v_fmaak_f32 v165, v165, v174, 0x358637bd
	v_fmaak_f32 v166, v166, v174, 0x358637bd
	v_fmaak_f32 v167, v167, v174, 0x358637bd
	v_rsq_f32_e32 v160, v160
	v_rsq_f32_e32 v161, v161
	v_rsq_f32_e32 v162, v162
	v_rsq_f32_e32 v163, v163
	v_rsq_f32_e32 v164, v164
	v_rsq_f32_e32 v165, v165
	v_rsq_f32_e32 v166, v166
	v_rsq_f32_e32 v167, v167
	v_readlane_b32 s84, v160, 63
	v_readlane_b32 s85, v161, 63
	v_readlane_b32 s86, v162, 63
	v_readlane_b32 s87, v163, 63
	v_readlane_b32 s88, v164, 63
	v_readlane_b32 s89, v165, 63
	v_readlane_b32 s90, v166, 63
	v_readlane_b32 s91, v167, 63
	s_waitcnt lgkmcnt(0)
	v_mul_f32_e32 v0, s84, v0
	v_mul_f32_e32 v1, s84, v1
	v_mul_f32_e32 v2, s84, v2
	v_mul_f32_e32 v3, s84, v3
	v_fma_f32 v0, v0, v178, v194
	v_fma_f32 v1, v1, v179, v195
	v_fma_f32 v2, v2, v180, v196
	v_fma_f32 v3, v3, v181, v197
	v_cvt_pk_bf16_f32 v0, v0, v1
	v_cvt_pk_bf16_f32 v1, v2, v3
	global_store_dwordx2 v169, v[0:1], s[10:11] offset:0
	v_mul_f32_e32 v4, s84, v4
	v_mul_f32_e32 v5, s84, v5
	v_mul_f32_e32 v6, s84, v6
	v_mul_f32_e32 v7, s84, v7
	v_fma_f32 v4, v4, v182, v198
	v_fma_f32 v5, v5, v183, v199
	v_fma_f32 v6, v6, v184, v200
	v_fma_f32 v7, v7, v185, v201
	v_cvt_pk_bf16_f32 v4, v4, v5
	v_cvt_pk_bf16_f32 v5, v6, v7
	global_store_dwordx2 v170, v[4:5], s[10:11] offset:0
	v_mul_f32_e32 v8, s84, v8
	v_mul_f32_e32 v9, s84, v9
	v_mul_f32_e32 v10, s84, v10
	v_mul_f32_e32 v11, s84, v11
	v_fma_f32 v8, v8, v186, v202
	v_fma_f32 v9, v9, v187, v203
	v_fma_f32 v10, v10, v188, v204
	v_fma_f32 v11, v11, v189, v205
	v_cvt_pk_bf16_f32 v8, v8, v9
	v_cvt_pk_bf16_f32 v9, v10, v11
	global_store_dwordx2 v171, v[8:9], s[10:11] offset:0
	v_mul_f32_e32 v12, s84, v12
	v_mul_f32_e32 v13, s84, v13
	v_mul_f32_e32 v14, s84, v14
	v_mul_f32_e32 v15, s84, v15
	v_fma_f32 v12, v12, v190, v206
	v_fma_f32 v13, v13, v191, v207
	v_fma_f32 v14, v14, v192, v208
	v_fma_f32 v15, v15, v193, v209
	v_cvt_pk_bf16_f32 v12, v12, v13
	v_cvt_pk_bf16_f32 v13, v14, v15
	global_store_dwordx2 v172, v[12:13], s[10:11] offset:0
	v_mul_f32_e32 v16, s85, v16
	v_mul_f32_e32 v17, s85, v17
	v_mul_f32_e32 v18, s85, v18
	v_mul_f32_e32 v19, s85, v19
	v_fma_f32 v16, v16, v178, v194
	v_fma_f32 v17, v17, v179, v195
	v_fma_f32 v18, v18, v180, v196
	v_fma_f32 v19, v19, v181, v197
	v_cvt_pk_bf16_f32 v16, v16, v17
	v_cvt_pk_bf16_f32 v17, v18, v19
	global_store_dwordx2 v169, v[16:17], s[10:11] offset:16
	v_mul_f32_e32 v20, s85, v20
	v_mul_f32_e32 v21, s85, v21
	v_mul_f32_e32 v22, s85, v22
	v_mul_f32_e32 v23, s85, v23
	v_fma_f32 v20, v20, v182, v198
	v_fma_f32 v21, v21, v183, v199
	v_fma_f32 v22, v22, v184, v200
	v_fma_f32 v23, v23, v185, v201
	v_cvt_pk_bf16_f32 v20, v20, v21
	v_cvt_pk_bf16_f32 v21, v22, v23
	global_store_dwordx2 v170, v[20:21], s[10:11] offset:16
	v_mul_f32_e32 v24, s85, v24
	v_mul_f32_e32 v25, s85, v25
	v_mul_f32_e32 v26, s85, v26
	v_mul_f32_e32 v27, s85, v27
	v_fma_f32 v24, v24, v186, v202
	v_fma_f32 v25, v25, v187, v203
	v_fma_f32 v26, v26, v188, v204
	v_fma_f32 v27, v27, v189, v205
	v_cvt_pk_bf16_f32 v24, v24, v25
	v_cvt_pk_bf16_f32 v25, v26, v27
	global_store_dwordx2 v171, v[24:25], s[10:11] offset:16
	v_mul_f32_e32 v28, s85, v28
	v_mul_f32_e32 v29, s85, v29
	v_mul_f32_e32 v30, s85, v30
	v_mul_f32_e32 v31, s85, v31
	v_fma_f32 v28, v28, v190, v206
	v_fma_f32 v29, v29, v191, v207
	v_fma_f32 v30, v30, v192, v208
	v_fma_f32 v31, v31, v193, v209
	v_cvt_pk_bf16_f32 v28, v28, v29
	v_cvt_pk_bf16_f32 v29, v30, v31
	global_store_dwordx2 v172, v[28:29], s[10:11] offset:16
	v_mul_f32_e32 v32, s86, v32
	v_mul_f32_e32 v33, s86, v33
	v_mul_f32_e32 v34, s86, v34
	v_mul_f32_e32 v35, s86, v35
	v_fma_f32 v32, v32, v178, v194
	v_fma_f32 v33, v33, v179, v195
	v_fma_f32 v34, v34, v180, v196
	v_fma_f32 v35, v35, v181, v197
	v_cvt_pk_bf16_f32 v32, v32, v33
	v_cvt_pk_bf16_f32 v33, v34, v35
	global_store_dwordx2 v169, v[32:33], s[10:11] offset:32
	v_mul_f32_e32 v36, s86, v36
	v_mul_f32_e32 v37, s86, v37
	v_mul_f32_e32 v38, s86, v38
	v_mul_f32_e32 v39, s86, v39
	v_fma_f32 v36, v36, v182, v198
	v_fma_f32 v37, v37, v183, v199
	v_fma_f32 v38, v38, v184, v200
	v_fma_f32 v39, v39, v185, v201
	v_cvt_pk_bf16_f32 v36, v36, v37
	v_cvt_pk_bf16_f32 v37, v38, v39
	global_store_dwordx2 v170, v[36:37], s[10:11] offset:32
	v_mul_f32_e32 v40, s86, v40
	v_mul_f32_e32 v41, s86, v41
	v_mul_f32_e32 v42, s86, v42
	v_mul_f32_e32 v43, s86, v43
	v_fma_f32 v40, v40, v186, v202
	v_fma_f32 v41, v41, v187, v203
	v_fma_f32 v42, v42, v188, v204
	v_fma_f32 v43, v43, v189, v205
	v_cvt_pk_bf16_f32 v40, v40, v41
	v_cvt_pk_bf16_f32 v41, v42, v43
	global_store_dwordx2 v171, v[40:41], s[10:11] offset:32
	v_mul_f32_e32 v44, s86, v44
	v_mul_f32_e32 v45, s86, v45
	v_mul_f32_e32 v46, s86, v46
	v_mul_f32_e32 v47, s86, v47
	v_fma_f32 v44, v44, v190, v206
	v_fma_f32 v45, v45, v191, v207
	v_fma_f32 v46, v46, v192, v208
	v_fma_f32 v47, v47, v193, v209
	v_cvt_pk_bf16_f32 v44, v44, v45
	v_cvt_pk_bf16_f32 v45, v46, v47
	global_store_dwordx2 v172, v[44:45], s[10:11] offset:32
	v_mul_f32_e32 v48, s87, v48
	v_mul_f32_e32 v49, s87, v49
	v_mul_f32_e32 v50, s87, v50
	v_mul_f32_e32 v51, s87, v51
	v_fma_f32 v48, v48, v178, v194
	v_fma_f32 v49, v49, v179, v195
	v_fma_f32 v50, v50, v180, v196
	v_fma_f32 v51, v51, v181, v197
	v_cvt_pk_bf16_f32 v48, v48, v49
	v_cvt_pk_bf16_f32 v49, v50, v51
	global_store_dwordx2 v169, v[48:49], s[10:11] offset:48
	v_mul_f32_e32 v52, s87, v52
	v_mul_f32_e32 v53, s87, v53
	v_mul_f32_e32 v54, s87, v54
	v_mul_f32_e32 v55, s87, v55
	v_fma_f32 v52, v52, v182, v198
	v_fma_f32 v53, v53, v183, v199
	v_fma_f32 v54, v54, v184, v200
	v_fma_f32 v55, v55, v185, v201
	v_cvt_pk_bf16_f32 v52, v52, v53
	v_cvt_pk_bf16_f32 v53, v54, v55
	global_store_dwordx2 v170, v[52:53], s[10:11] offset:48
	v_mul_f32_e32 v56, s87, v56
	v_mul_f32_e32 v57, s87, v57
	v_mul_f32_e32 v58, s87, v58
	v_mul_f32_e32 v59, s87, v59
	v_fma_f32 v56, v56, v186, v202
	v_fma_f32 v57, v57, v187, v203
	v_fma_f32 v58, v58, v188, v204
	v_fma_f32 v59, v59, v189, v205
	v_cvt_pk_bf16_f32 v56, v56, v57
	v_cvt_pk_bf16_f32 v57, v58, v59
	global_store_dwordx2 v171, v[56:57], s[10:11] offset:48
	v_mul_f32_e32 v60, s87, v60
	v_mul_f32_e32 v61, s87, v61
	v_mul_f32_e32 v62, s87, v62
	v_mul_f32_e32 v63, s87, v63
	v_fma_f32 v60, v60, v190, v206
	v_fma_f32 v61, v61, v191, v207
	v_fma_f32 v62, v62, v192, v208
	v_fma_f32 v63, v63, v193, v209
	v_cvt_pk_bf16_f32 v60, v60, v61
	v_cvt_pk_bf16_f32 v61, v62, v63
	global_store_dwordx2 v172, v[60:61], s[10:11] offset:48
	v_mul_f32_e32 v64, s88, v64
	v_mul_f32_e32 v65, s88, v65
	v_mul_f32_e32 v66, s88, v66
	v_mul_f32_e32 v67, s88, v67
	v_fma_f32 v64, v64, v178, v194
	v_fma_f32 v65, v65, v179, v195
	v_fma_f32 v66, v66, v180, v196
	v_fma_f32 v67, v67, v181, v197
	v_cvt_pk_bf16_f32 v64, v64, v65
	v_cvt_pk_bf16_f32 v65, v66, v67
	global_store_dwordx2 v169, v[64:65], s[10:11] offset:64
	v_mul_f32_e32 v68, s88, v68
	v_mul_f32_e32 v69, s88, v69
	v_mul_f32_e32 v70, s88, v70
	v_mul_f32_e32 v71, s88, v71
	v_fma_f32 v68, v68, v182, v198
	v_fma_f32 v69, v69, v183, v199
	v_fma_f32 v70, v70, v184, v200
	v_fma_f32 v71, v71, v185, v201
	v_cvt_pk_bf16_f32 v68, v68, v69
	v_cvt_pk_bf16_f32 v69, v70, v71
	global_store_dwordx2 v170, v[68:69], s[10:11] offset:64
	v_mul_f32_e32 v72, s88, v72
	v_mul_f32_e32 v73, s88, v73
	v_mul_f32_e32 v74, s88, v74
	v_mul_f32_e32 v75, s88, v75
	v_fma_f32 v72, v72, v186, v202
	v_fma_f32 v73, v73, v187, v203
	v_fma_f32 v74, v74, v188, v204
	v_fma_f32 v75, v75, v189, v205
	v_cvt_pk_bf16_f32 v72, v72, v73
	v_cvt_pk_bf16_f32 v73, v74, v75
	global_store_dwordx2 v171, v[72:73], s[10:11] offset:64
	v_mul_f32_e32 v76, s88, v76
	v_mul_f32_e32 v77, s88, v77
	v_mul_f32_e32 v78, s88, v78
	v_mul_f32_e32 v79, s88, v79
	v_fma_f32 v76, v76, v190, v206
	v_fma_f32 v77, v77, v191, v207
	v_fma_f32 v78, v78, v192, v208
	v_fma_f32 v79, v79, v193, v209
	v_cvt_pk_bf16_f32 v76, v76, v77
	v_cvt_pk_bf16_f32 v77, v78, v79
	global_store_dwordx2 v172, v[76:77], s[10:11] offset:64
	v_mul_f32_e32 v80, s89, v80
	v_mul_f32_e32 v81, s89, v81
	v_mul_f32_e32 v82, s89, v82
	v_mul_f32_e32 v83, s89, v83
	v_fma_f32 v80, v80, v178, v194
	v_fma_f32 v81, v81, v179, v195
	v_fma_f32 v82, v82, v180, v196
	v_fma_f32 v83, v83, v181, v197
	v_cvt_pk_bf16_f32 v80, v80, v81
	v_cvt_pk_bf16_f32 v81, v82, v83
	global_store_dwordx2 v169, v[80:81], s[10:11] offset:80
	v_mul_f32_e32 v84, s89, v84
	v_mul_f32_e32 v85, s89, v85
	v_mul_f32_e32 v86, s89, v86
	v_mul_f32_e32 v87, s89, v87
	v_fma_f32 v84, v84, v182, v198
	v_fma_f32 v85, v85, v183, v199
	v_fma_f32 v86, v86, v184, v200
	v_fma_f32 v87, v87, v185, v201
	v_cvt_pk_bf16_f32 v84, v84, v85
	v_cvt_pk_bf16_f32 v85, v86, v87
	global_store_dwordx2 v170, v[84:85], s[10:11] offset:80
	v_mul_f32_e32 v88, s89, v88
	v_mul_f32_e32 v89, s89, v89
	v_mul_f32_e32 v90, s89, v90
	v_mul_f32_e32 v91, s89, v91
	v_fma_f32 v88, v88, v186, v202
	v_fma_f32 v89, v89, v187, v203
	v_fma_f32 v90, v90, v188, v204
	v_fma_f32 v91, v91, v189, v205
	v_cvt_pk_bf16_f32 v88, v88, v89
	v_cvt_pk_bf16_f32 v89, v90, v91
	global_store_dwordx2 v171, v[88:89], s[10:11] offset:80
	v_mul_f32_e32 v92, s89, v92
	v_mul_f32_e32 v93, s89, v93
	v_mul_f32_e32 v94, s89, v94
	v_mul_f32_e32 v95, s89, v95
	v_fma_f32 v92, v92, v190, v206
	v_fma_f32 v93, v93, v191, v207
	v_fma_f32 v94, v94, v192, v208
	v_fma_f32 v95, v95, v193, v209
	v_cvt_pk_bf16_f32 v92, v92, v93
	v_cvt_pk_bf16_f32 v93, v94, v95
	global_store_dwordx2 v172, v[92:93], s[10:11] offset:80
	v_mul_f32_e32 v96, s90, v96
	v_mul_f32_e32 v97, s90, v97
	v_mul_f32_e32 v98, s90, v98
	v_mul_f32_e32 v99, s90, v99
	v_fma_f32 v96, v96, v178, v194
	v_fma_f32 v97, v97, v179, v195
	v_fma_f32 v98, v98, v180, v196
	v_fma_f32 v99, v99, v181, v197
	v_cvt_pk_bf16_f32 v96, v96, v97
	v_cvt_pk_bf16_f32 v97, v98, v99
	global_store_dwordx2 v169, v[96:97], s[10:11] offset:96
	v_mul_f32_e32 v100, s90, v100
	v_mul_f32_e32 v101, s90, v101
	v_mul_f32_e32 v102, s90, v102
	v_mul_f32_e32 v103, s90, v103
	v_fma_f32 v100, v100, v182, v198
	v_fma_f32 v101, v101, v183, v199
	v_fma_f32 v102, v102, v184, v200
	v_fma_f32 v103, v103, v185, v201
	v_cvt_pk_bf16_f32 v100, v100, v101
	v_cvt_pk_bf16_f32 v101, v102, v103
	global_store_dwordx2 v170, v[100:101], s[10:11] offset:96
	v_mul_f32_e32 v104, s90, v104
	v_mul_f32_e32 v105, s90, v105
	v_mul_f32_e32 v106, s90, v106
	v_mul_f32_e32 v107, s90, v107
	v_fma_f32 v104, v104, v186, v202
	v_fma_f32 v105, v105, v187, v203
	v_fma_f32 v106, v106, v188, v204
	v_fma_f32 v107, v107, v189, v205
	v_cvt_pk_bf16_f32 v104, v104, v105
	v_cvt_pk_bf16_f32 v105, v106, v107
	global_store_dwordx2 v171, v[104:105], s[10:11] offset:96
	v_mul_f32_e32 v108, s90, v108
	v_mul_f32_e32 v109, s90, v109
	v_mul_f32_e32 v110, s90, v110
	v_mul_f32_e32 v111, s90, v111
	v_fma_f32 v108, v108, v190, v206
	v_fma_f32 v109, v109, v191, v207
	v_fma_f32 v110, v110, v192, v208
	v_fma_f32 v111, v111, v193, v209
	v_cvt_pk_bf16_f32 v108, v108, v109
	v_cvt_pk_bf16_f32 v109, v110, v111
	global_store_dwordx2 v172, v[108:109], s[10:11] offset:96
	v_mul_f32_e32 v112, s91, v112
	v_mul_f32_e32 v113, s91, v113
	v_mul_f32_e32 v114, s91, v114
	v_mul_f32_e32 v115, s91, v115
	v_fma_f32 v112, v112, v178, v194
	v_fma_f32 v113, v113, v179, v195
	v_fma_f32 v114, v114, v180, v196
	v_fma_f32 v115, v115, v181, v197
	v_cvt_pk_bf16_f32 v112, v112, v113
	v_cvt_pk_bf16_f32 v113, v114, v115
	global_store_dwordx2 v169, v[112:113], s[10:11] offset:112
	v_mul_f32_e32 v116, s91, v116
	v_mul_f32_e32 v117, s91, v117
	v_mul_f32_e32 v118, s91, v118
	v_mul_f32_e32 v119, s91, v119
	v_fma_f32 v116, v116, v182, v198
	v_fma_f32 v117, v117, v183, v199
	v_fma_f32 v118, v118, v184, v200
	v_fma_f32 v119, v119, v185, v201
	v_cvt_pk_bf16_f32 v116, v116, v117
	v_cvt_pk_bf16_f32 v117, v118, v119
	global_store_dwordx2 v170, v[116:117], s[10:11] offset:112
	v_mul_f32_e32 v120, s91, v120
	v_mul_f32_e32 v121, s91, v121
	v_mul_f32_e32 v122, s91, v122
	v_mul_f32_e32 v123, s91, v123
	v_fma_f32 v120, v120, v186, v202
	v_fma_f32 v121, v121, v187, v203
	v_fma_f32 v122, v122, v188, v204
	v_fma_f32 v123, v123, v189, v205
	v_cvt_pk_bf16_f32 v120, v120, v121
	v_cvt_pk_bf16_f32 v121, v122, v123
	global_store_dwordx2 v171, v[120:121], s[10:11] offset:112
	v_mul_f32_e32 v124, s91, v124
	v_mul_f32_e32 v125, s91, v125
	v_mul_f32_e32 v126, s91, v126
	v_mul_f32_e32 v127, s91, v127
	v_fma_f32 v124, v124, v190, v206
	v_fma_f32 v125, v125, v191, v207
	v_fma_f32 v126, v126, v192, v208
	v_fma_f32 v127, v127, v193, v209
	v_cvt_pk_bf16_f32 v124, v124, v125
	v_cvt_pk_bf16_f32 v125, v126, v127
	global_store_dwordx2 v172, v[124:125], s[10:11] offset:112
	s_add_i32 s4, s4, s3
	s_cmpk_lt_i32 s4, 0x200
	s_cbranch_scc1 .Lmy_hdn0_loop

.LBB0_171:
	s_ashr_i32 s1, s75, 31
	s_lshr_b32 s1, s1, 23
	s_add_i32 s1, s75, s1
	s_ashr_i32 s1, s1, 9
	s_and_b32 s0, s75, 7
	s_lshl_b32 s1, s1, 3
	s_or_b32 s34, s1, s0
	s_mul_hi_i32 s0, s34, 0x92492493
	s_add_i32 s0, s0, s34
	s_lshr_b32 s1, s0, 31
	s_ashr_i32 s70, s0, 2
	s_add_i32 s70, s70, s1
	s_lshl_b32 s0, s70, 3
	s_bfe_u32 s1, s75, 0x30003
	s_or_b32 s66, s0, s1
	s_mul_i32 s0, s70, 7
	s_sub_i32 s77, s34, s0
	s_lshl_b32 s0, s77, 3
	s_bfe_u32 s76, s75, 0x30006
	s_or_b32 s0, s0, s76
	s_ashr_i32 s67, s66, 31
	s_ashr_i32 s1, s0, 31
	s_lshl_b64 s[4:5], s[0:1], 18
	s_lshl_b64 s[6:7], s[66:67], 18
	s_barrier
	s_lshl_b64 s[64:65], s[66:67], 17
	s_add_u32 s84, s50, 0x3a00000
	s_addc_u32 s85, s51, 0
	s_add_u32 s84, s84, s6
	s_addc_u32 s85, s85, s7
	s_add_u32 s86, s50, 0x1a00000
	s_addc_u32 s87, s51, 0
	s_add_u32 s86, s86, s4
	s_addc_u32 s87, s87, s5
	v_readfirstlane_b32 s1, v129
	v_and_b32_e32 v112, 15, v131
	v_bfe_u32 v113, v131, 4, 2
	v_and_b32_e32 v114, 63, v131
	v_lshlrev_b32_e32 v114, 4, v114
	v_lshrrev_b32_e32 v115, 6, v131
	v_lshl_add_u32 v142, v115, 16, v114
	v_add_u32_e32 v216, 0x8000, v142
	v_bfe_u32 v114, v131, 1, 3
	v_xor_b32_e32 v114, v113, v114
	v_lshlrev_b32_e32 v114, 4, v114
	v_lshl_or_b32 v226, v112, 7, v114
	v_xor_b32_e32 v228, 64, v226
	v_bfe_u32 v112, v131, 4, 3
	v_and_b32_e32 v113, 7, v131
	v_xor_b32_e32 v112, v112, v113
	v_lshlrev_b32_e32 v112, 4, v112
	v_lshrrev_b32_e32 v113, 3, v131
	v_lshl_or_b32 v218, v113, 11, v112
	v_add_u32_e32 v220, 65536, v218
	v_add_u32_e32 v222, 131072, v218
	v_add_u32_e32 v224, 196608, v218
	s_add_u32 m0, s1, 0
	v_mov_b32_e32 v0, 0
	v_mov_b32_e32 v1, 0
	global_load_lds_dwordx4 v218, s[86:87]
	v_mov_b32_e32 v2, 0
	v_mov_b32_e32 v3, 0
	s_add_u32 m0, s1, 4096
	v_mov_b32_e32 v4, 0
	v_mov_b32_e32 v5, 0
	global_load_lds_dwordx4 v220, s[86:87]
	v_mov_b32_e32 v6, 0
	v_mov_b32_e32 v7, 0
	s_add_u32 m0, s1, 8192
	v_mov_b32_e32 v8, 0
	v_mov_b32_e32 v9, 0
	global_load_lds_dwordx4 v222, s[86:87]
	v_mov_b32_e32 v10, 0
	v_mov_b32_e32 v11, 0
	s_add_u32 m0, s1, 12288
	v_mov_b32_e32 v12, 0
	v_mov_b32_e32 v13, 0
	global_load_lds_dwordx4 v224, s[86:87]
	s_add_u32 s86, s86, 128
	s_addc_u32 s87, s87, 0
	v_mov_b32_e32 v14, 0
	v_mov_b32_e32 v15, 0
	global_load_dwordx4 v[64:67], v142, s[84:85] offset:0
	v_mov_b32_e32 v16, 0
	v_mov_b32_e32 v17, 0
	global_load_dwordx4 v[68:71], v142, s[84:85] offset:1024
	v_mov_b32_e32 v18, 0
	v_mov_b32_e32 v19, 0
	global_load_dwordx4 v[72:75], v216, s[84:85] offset:0
	v_mov_b32_e32 v20, 0
	v_mov_b32_e32 v21, 0
	global_load_dwordx4 v[76:79], v216, s[84:85] offset:1024
	s_add_u32 s84, s84, 0x800
	s_addc_u32 s85, s85, 0
	v_mov_b32_e32 v22, 0
	v_mov_b32_e32 v23, 0
	s_add_u32 m0, s1, 16384
	v_mov_b32_e32 v24, 0
	v_mov_b32_e32 v25, 0
	global_load_lds_dwordx4 v218, s[86:87]
	v_mov_b32_e32 v26, 0
	v_mov_b32_e32 v27, 0
	s_add_u32 m0, s1, 20480
	v_mov_b32_e32 v28, 0
	v_mov_b32_e32 v29, 0
	global_load_lds_dwordx4 v220, s[86:87]
	v_mov_b32_e32 v30, 0
	v_mov_b32_e32 v31, 0
	s_add_u32 m0, s1, 24576
	v_mov_b32_e32 v32, 0
	v_mov_b32_e32 v33, 0
	global_load_lds_dwordx4 v222, s[86:87]
	v_mov_b32_e32 v34, 0
	v_mov_b32_e32 v35, 0
	s_add_u32 m0, s1, 28672
	v_mov_b32_e32 v36, 0
	v_mov_b32_e32 v37, 0
	global_load_lds_dwordx4 v224, s[86:87]
	s_add_u32 s86, s86, 128
	s_addc_u32 s87, s87, 0
	v_mov_b32_e32 v38, 0
	v_mov_b32_e32 v39, 0
	global_load_dwordx4 v[80:83], v142, s[84:85] offset:0
	v_mov_b32_e32 v40, 0
	v_mov_b32_e32 v41, 0
	global_load_dwordx4 v[84:87], v142, s[84:85] offset:1024
	v_mov_b32_e32 v42, 0
	v_mov_b32_e32 v43, 0
	global_load_dwordx4 v[88:91], v216, s[84:85] offset:0
	v_mov_b32_e32 v44, 0
	v_mov_b32_e32 v45, 0
	global_load_dwordx4 v[92:95], v216, s[84:85] offset:1024
	s_add_u32 s84, s84, 0x800
	s_addc_u32 s85, s85, 0
	v_mov_b32_e32 v46, 0
	v_mov_b32_e32 v47, 0
	s_add_u32 m0, s1, 32768
	v_mov_b32_e32 v48, 0
	v_mov_b32_e32 v49, 0
	global_load_lds_dwordx4 v218, s[86:87]
	v_mov_b32_e32 v50, 0
	v_mov_b32_e32 v51, 0
	s_add_u32 m0, s1, 36864
	v_mov_b32_e32 v52, 0
	v_mov_b32_e32 v53, 0
	global_load_lds_dwordx4 v220, s[86:87]
	v_mov_b32_e32 v54, 0
	v_mov_b32_e32 v55, 0
	s_add_u32 m0, s1, 40960
	v_mov_b32_e32 v56, 0
	v_mov_b32_e32 v57, 0
	global_load_lds_dwordx4 v222, s[86:87]
	v_mov_b32_e32 v58, 0
	v_mov_b32_e32 v59, 0
	s_add_u32 m0, s1, 45056
	v_mov_b32_e32 v60, 0
	v_mov_b32_e32 v61, 0
	global_load_lds_dwordx4 v224, s[86:87]
	s_add_u32 s86, s86, 128
	s_addc_u32 s87, s87, 0
	v_mov_b32_e32 v62, 0
	v_mov_b32_e32 v63, 0
	s_waitcnt vmcnt(12)
	s_barrier
	ds_read_b128 v[112:115], v226 offset:0
	ds_read_b128 v[116:119], v226 offset:2048
	ds_read_b128 v[120:123], v226 offset:4096
	ds_read_b128 v[124:127], v226 offset:6144
	ds_read_b128 v[200:203], v226 offset:8192
	ds_read_b128 v[204:207], v226 offset:10240
	ds_read_b128 v[208:211], v226 offset:12288
	s_waitcnt lgkmcnt(6)
	v_mfma_f32_16x16x32_bf16 v[0:3], v[64:67], v[112:115], v[0:3]
	v_mfma_f32_16x16x32_bf16 v[32:35], v[72:75], v[112:115], v[32:35]
	ds_read_b128 v[212:215], v226 offset:14336
	s_waitcnt lgkmcnt(6)
	v_mfma_f32_16x16x32_bf16 v[4:7], v[64:67], v[116:119], v[4:7]
	v_mfma_f32_16x16x32_bf16 v[36:39], v[72:75], v[116:119], v[36:39]
	ds_read_b128 v[230:233], v228 offset:0
	s_waitcnt lgkmcnt(6)
	v_mfma_f32_16x16x32_bf16 v[8:11], v[64:67], v[120:123], v[8:11]
	v_mfma_f32_16x16x32_bf16 v[40:43], v[72:75], v[120:123], v[40:43]
	ds_read_b128 v[234:237], v228 offset:2048
	s_waitcnt lgkmcnt(6)
	v_mfma_f32_16x16x32_bf16 v[12:15], v[64:67], v[124:127], v[12:15]
	v_mfma_f32_16x16x32_bf16 v[44:47], v[72:75], v[124:127], v[44:47]
	ds_read_b128 v[238:241], v228 offset:4096
	s_waitcnt lgkmcnt(6)
	v_mfma_f32_16x16x32_bf16 v[16:19], v[64:67], v[200:203], v[16:19]
	v_mfma_f32_16x16x32_bf16 v[48:51], v[72:75], v[200:203], v[48:51]
	ds_read_b128 v[242:245], v228 offset:6144
	s_waitcnt lgkmcnt(6)
	v_mfma_f32_16x16x32_bf16 v[20:23], v[64:67], v[204:207], v[20:23]
	v_mfma_f32_16x16x32_bf16 v[52:55], v[72:75], v[204:207], v[52:55]
	ds_read_b128 v[112:115], v228 offset:8192
	s_waitcnt lgkmcnt(6)
	v_mfma_f32_16x16x32_bf16 v[24:27], v[64:67], v[208:211], v[24:27]
	v_mfma_f32_16x16x32_bf16 v[56:59], v[72:75], v[208:211], v[56:59]
	ds_read_b128 v[116:119], v228 offset:10240
	s_waitcnt lgkmcnt(6)
	v_mfma_f32_16x16x32_bf16 v[28:31], v[64:67], v[212:215], v[28:31]
	v_mfma_f32_16x16x32_bf16 v[60:63], v[72:75], v[212:215], v[60:63]
	s_waitcnt vmcnt(8)
	s_barrier
	ds_read_b128 v[120:123], v228 offset:12288
	global_load_dwordx4 v[96:99], v142, s[84:85] offset:0
	s_waitcnt lgkmcnt(6)
	v_mfma_f32_16x16x32_bf16 v[0:3], v[68:71], v[230:233], v[0:3]
	v_mfma_f32_16x16x32_bf16 v[32:35], v[76:79], v[230:233], v[32:35]
	ds_read_b128 v[124:127], v228 offset:14336
	global_load_dwordx4 v[100:103], v142, s[84:85] offset:1024
	s_waitcnt lgkmcnt(6)
	v_mfma_f32_16x16x32_bf16 v[4:7], v[68:71], v[234:237], v[4:7]
	v_mfma_f32_16x16x32_bf16 v[36:39], v[76:79], v[234:237], v[36:39]
	ds_read_b128 v[200:203], v226 offset:16384
	global_load_dwordx4 v[104:107], v216, s[84:85] offset:0
	s_waitcnt lgkmcnt(6)
	v_mfma_f32_16x16x32_bf16 v[8:11], v[68:71], v[238:241], v[8:11]
	v_mfma_f32_16x16x32_bf16 v[40:43], v[76:79], v[238:241], v[40:43]
	ds_read_b128 v[204:207], v226 offset:18432
	global_load_dwordx4 v[108:111], v216, s[84:85] offset:1024
	s_add_u32 s84, s84, 0x800
	s_addc_u32 s85, s85, 0
	s_waitcnt lgkmcnt(6)
	v_mfma_f32_16x16x32_bf16 v[12:15], v[68:71], v[242:245], v[12:15]
	v_mfma_f32_16x16x32_bf16 v[44:47], v[76:79], v[242:245], v[44:47]
	ds_read_b128 v[208:211], v226 offset:20480
	s_add_u32 m0, s1, 49152
	s_nop 0
	global_load_lds_dwordx4 v218, s[86:87]
	s_waitcnt lgkmcnt(6)
	v_mfma_f32_16x16x32_bf16 v[16:19], v[68:71], v[112:115], v[16:19]
	v_mfma_f32_16x16x32_bf16 v[48:51], v[76:79], v[112:115], v[48:51]
	ds_read_b128 v[212:215], v226 offset:22528
	s_add_u32 m0, s1, 53248
	s_nop 0
	global_load_lds_dwordx4 v220, s[86:87]
	s_waitcnt lgkmcnt(6)
	v_mfma_f32_16x16x32_bf16 v[20:23], v[68:71], v[116:119], v[20:23]
	v_mfma_f32_16x16x32_bf16 v[52:55], v[76:79], v[116:119], v[52:55]
	ds_read_b128 v[230:233], v226 offset:24576
	s_add_u32 m0, s1, 57344
	s_nop 0
	global_load_lds_dwordx4 v222, s[86:87]
	s_waitcnt lgkmcnt(6)
	v_mfma_f32_16x16x32_bf16 v[24:27], v[68:71], v[120:123], v[24:27]
	v_mfma_f32_16x16x32_bf16 v[56:59], v[76:79], v[120:123], v[56:59]
	ds_read_b128 v[234:237], v226 offset:26624
	s_add_u32 m0, s1, 61440
	s_nop 0
	global_load_lds_dwordx4 v224, s[86:87]
	s_add_u32 s86, s86, 128
	s_addc_u32 s87, s87, 0
	s_waitcnt lgkmcnt(6)
	v_mfma_f32_16x16x32_bf16 v[28:31], v[68:71], v[124:127], v[28:31]
	v_mfma_f32_16x16x32_bf16 v[60:63], v[76:79], v[124:127], v[60:63]
	s_waitcnt vmcnt(12)
	ds_read_b128 v[238:241], v226 offset:28672
	s_waitcnt lgkmcnt(6)
	v_mfma_f32_16x16x32_bf16 v[0:3], v[80:83], v[200:203], v[0:3]
	v_mfma_f32_16x16x32_bf16 v[32:35], v[88:91], v[200:203], v[32:35]
	ds_read_b128 v[242:245], v226 offset:30720
	s_waitcnt lgkmcnt(6)
	v_mfma_f32_16x16x32_bf16 v[4:7], v[80:83], v[204:207], v[4:7]
	v_mfma_f32_16x16x32_bf16 v[36:39], v[88:91], v[204:207], v[36:39]
	ds_read_b128 v[112:115], v228 offset:16384
	s_waitcnt lgkmcnt(6)
	v_mfma_f32_16x16x32_bf16 v[8:11], v[80:83], v[208:211], v[8:11]
	v_mfma_f32_16x16x32_bf16 v[40:43], v[88:91], v[208:211], v[40:43]
	ds_read_b128 v[116:119], v228 offset:18432
	s_waitcnt lgkmcnt(6)
	v_mfma_f32_16x16x32_bf16 v[12:15], v[80:83], v[212:215], v[12:15]
	v_mfma_f32_16x16x32_bf16 v[44:47], v[88:91], v[212:215], v[44:47]
	ds_read_b128 v[120:123], v228 offset:20480
	s_waitcnt lgkmcnt(6)
	v_mfma_f32_16x16x32_bf16 v[16:19], v[80:83], v[230:233], v[16:19]
	v_mfma_f32_16x16x32_bf16 v[48:51], v[88:91], v[230:233], v[48:51]
	ds_read_b128 v[124:127], v228 offset:22528
	s_waitcnt lgkmcnt(6)
	v_mfma_f32_16x16x32_bf16 v[20:23], v[80:83], v[234:237], v[20:23]
	v_mfma_f32_16x16x32_bf16 v[52:55], v[88:91], v[234:237], v[52:55]
	ds_read_b128 v[200:203], v228 offset:24576
	s_waitcnt lgkmcnt(6)
	v_mfma_f32_16x16x32_bf16 v[24:27], v[80:83], v[238:241], v[24:27]
	v_mfma_f32_16x16x32_bf16 v[56:59], v[88:91], v[238:241], v[56:59]
	ds_read_b128 v[204:207], v228 offset:26624
	s_waitcnt lgkmcnt(6)
	v_mfma_f32_16x16x32_bf16 v[28:31], v[80:83], v[242:245], v[28:31]
	v_mfma_f32_16x16x32_bf16 v[60:63], v[88:91], v[242:245], v[60:63]
	s_waitcnt vmcnt(8)
	s_barrier
	ds_read_b128 v[208:211], v228 offset:28672
	global_load_dwordx4 v[64:67], v142, s[84:85] offset:0
	s_waitcnt lgkmcnt(6)
	v_mfma_f32_16x16x32_bf16 v[0:3], v[84:87], v[112:115], v[0:3]
	v_mfma_f32_16x16x32_bf16 v[32:35], v[92:95], v[112:115], v[32:35]
	ds_read_b128 v[212:215], v228 offset:30720
	global_load_dwordx4 v[68:71], v142, s[84:85] offset:1024
	s_waitcnt lgkmcnt(6)
	v_mfma_f32_16x16x32_bf16 v[4:7], v[84:87], v[116:119], v[4:7]
	v_mfma_f32_16x16x32_bf16 v[36:39], v[92:95], v[116:119], v[36:39]
	ds_read_b128 v[230:233], v226 offset:32768
	global_load_dwordx4 v[72:75], v216, s[84:85] offset:0
	s_waitcnt lgkmcnt(6)
	v_mfma_f32_16x16x32_bf16 v[8:11], v[84:87], v[120:123], v[8:11]
	v_mfma_f32_16x16x32_bf16 v[40:43], v[92:95], v[120:123], v[40:43]
	ds_read_b128 v[234:237], v226 offset:34816
	global_load_dwordx4 v[76:79], v216, s[84:85] offset:1024
	s_add_u32 s84, s84, 0x800
	s_addc_u32 s85, s85, 0
	s_waitcnt lgkmcnt(6)
	v_mfma_f32_16x16x32_bf16 v[12:15], v[84:87], v[124:127], v[12:15]
	v_mfma_f32_16x16x32_bf16 v[44:47], v[92:95], v[124:127], v[44:47]
	ds_read_b128 v[238:241], v226 offset:36864
	s_add_u32 m0, s1, 0
	s_nop 0
	global_load_lds_dwordx4 v218, s[86:87]
	s_waitcnt lgkmcnt(6)
	v_mfma_f32_16x16x32_bf16 v[16:19], v[84:87], v[200:203], v[16:19]
	v_mfma_f32_16x16x32_bf16 v[48:51], v[92:95], v[200:203], v[48:51]
	ds_read_b128 v[242:245], v226 offset:38912
	s_add_u32 m0, s1, 4096
	s_nop 0
	global_load_lds_dwordx4 v220, s[86:87]
	s_waitcnt lgkmcnt(6)
	v_mfma_f32_16x16x32_bf16 v[20:23], v[84:87], v[204:207], v[20:23]
	v_mfma_f32_16x16x32_bf16 v[52:55], v[92:95], v[204:207], v[52:55]
	ds_read_b128 v[112:115], v226 offset:40960
	s_add_u32 m0, s1, 8192
	s_nop 0
	global_load_lds_dwordx4 v222, s[86:87]
	s_waitcnt lgkmcnt(6)
	v_mfma_f32_16x16x32_bf16 v[24:27], v[84:87], v[208:211], v[24:27]
	v_mfma_f32_16x16x32_bf16 v[56:59], v[92:95], v[208:211], v[56:59]
	ds_read_b128 v[116:119], v226 offset:43008
	s_add_u32 m0, s1, 12288
	s_nop 0
	global_load_lds_dwordx4 v224, s[86:87]
	s_add_u32 s86, s86, 128
	s_addc_u32 s87, s87, 0
	s_waitcnt lgkmcnt(6)
	v_mfma_f32_16x16x32_bf16 v[28:31], v[84:87], v[212:215], v[28:31]
	v_mfma_f32_16x16x32_bf16 v[60:63], v[92:95], v[212:215], v[60:63]
	s_waitcnt vmcnt(12)
	ds_read_b128 v[120:123], v226 offset:45056
	s_waitcnt lgkmcnt(6)
	v_mfma_f32_16x16x32_bf16 v[0:3], v[96:99], v[230:233], v[0:3]
	v_mfma_f32_16x16x32_bf16 v[32:35], v[104:107], v[230:233], v[32:35]
	ds_read_b128 v[124:127], v226 offset:47104
	s_waitcnt lgkmcnt(6)
	v_mfma_f32_16x16x32_bf16 v[4:7], v[96:99], v[234:237], v[4:7]
	v_mfma_f32_16x16x32_bf16 v[36:39], v[104:107], v[234:237], v[36:39]
	ds_read_b128 v[200:203], v228 offset:32768
	s_waitcnt lgkmcnt(6)
	v_mfma_f32_16x16x32_bf16 v[8:11], v[96:99], v[238:241], v[8:11]
	v_mfma_f32_16x16x32_bf16 v[40:43], v[104:107], v[238:241], v[40:43]
	ds_read_b128 v[204:207], v228 offset:34816
	s_waitcnt lgkmcnt(6)
	v_mfma_f32_16x16x32_bf16 v[12:15], v[96:99], v[242:245], v[12:15]
	v_mfma_f32_16x16x32_bf16 v[44:47], v[104:107], v[242:245], v[44:47]
	ds_read_b128 v[208:211], v228 offset:36864
	s_waitcnt lgkmcnt(6)
	v_mfma_f32_16x16x32_bf16 v[16:19], v[96:99], v[112:115], v[16:19]
	v_mfma_f32_16x16x32_bf16 v[48:51], v[104:107], v[112:115], v[48:51]
	ds_read_b128 v[212:215], v228 offset:38912
	s_waitcnt lgkmcnt(6)
	v_mfma_f32_16x16x32_bf16 v[20:23], v[96:99], v[116:119], v[20:23]
	v_mfma_f32_16x16x32_bf16 v[52:55], v[104:107], v[116:119], v[52:55]
	ds_read_b128 v[230:233], v228 offset:40960
	s_waitcnt lgkmcnt(6)
	v_mfma_f32_16x16x32_bf16 v[24:27], v[96:99], v[120:123], v[24:27]
	v_mfma_f32_16x16x32_bf16 v[56:59], v[104:107], v[120:123], v[56:59]
	ds_read_b128 v[234:237], v228 offset:43008
	s_waitcnt lgkmcnt(6)
	v_mfma_f32_16x16x32_bf16 v[28:31], v[96:99], v[124:127], v[28:31]
	v_mfma_f32_16x16x32_bf16 v[60:63], v[104:107], v[124:127], v[60:63]
	s_waitcnt vmcnt(8)
	s_barrier
	ds_read_b128 v[238:241], v228 offset:45056
	global_load_dwordx4 v[80:83], v142, s[84:85] offset:0
	s_waitcnt lgkmcnt(6)
	v_mfma_f32_16x16x32_bf16 v[0:3], v[100:103], v[200:203], v[0:3]
	v_mfma_f32_16x16x32_bf16 v[32:35], v[108:111], v[200:203], v[32:35]
	ds_read_b128 v[242:245], v228 offset:47104
	global_load_dwordx4 v[84:87], v142, s[84:85] offset:1024
	s_waitcnt lgkmcnt(6)
	v_mfma_f32_16x16x32_bf16 v[4:7], v[100:103], v[204:207], v[4:7]
	v_mfma_f32_16x16x32_bf16 v[36:39], v[108:111], v[204:207], v[36:39]
	ds_read_b128 v[112:115], v226 offset:49152
	global_load_dwordx4 v[88:91], v216, s[84:85] offset:0
	s_waitcnt lgkmcnt(6)
	v_mfma_f32_16x16x32_bf16 v[8:11], v[100:103], v[208:211], v[8:11]
	v_mfma_f32_16x16x32_bf16 v[40:43], v[108:111], v[208:211], v[40:43]
	ds_read_b128 v[116:119], v226 offset:51200
	global_load_dwordx4 v[92:95], v216, s[84:85] offset:1024
	s_add_u32 s84, s84, 0x800
	s_addc_u32 s85, s85, 0
	s_waitcnt lgkmcnt(6)
	v_mfma_f32_16x16x32_bf16 v[12:15], v[100:103], v[212:215], v[12:15]
	v_mfma_f32_16x16x32_bf16 v[44:47], v[108:111], v[212:215], v[44:47]
	ds_read_b128 v[120:123], v226 offset:53248
	s_add_u32 m0, s1, 16384
	s_nop 0
	global_load_lds_dwordx4 v218, s[86:87]
	s_waitcnt lgkmcnt(6)
	v_mfma_f32_16x16x32_bf16 v[16:19], v[100:103], v[230:233], v[16:19]
	v_mfma_f32_16x16x32_bf16 v[48:51], v[108:111], v[230:233], v[48:51]
	ds_read_b128 v[124:127], v226 offset:55296
	s_add_u32 m0, s1, 20480
	s_nop 0
	global_load_lds_dwordx4 v220, s[86:87]
	s_waitcnt lgkmcnt(6)
	v_mfma_f32_16x16x32_bf16 v[20:23], v[100:103], v[234:237], v[20:23]
	v_mfma_f32_16x16x32_bf16 v[52:55], v[108:111], v[234:237], v[52:55]
	ds_read_b128 v[200:203], v226 offset:57344
	s_add_u32 m0, s1, 24576
	s_nop 0
	global_load_lds_dwordx4 v222, s[86:87]
	s_waitcnt lgkmcnt(6)
	v_mfma_f32_16x16x32_bf16 v[24:27], v[100:103], v[238:241], v[24:27]
	v_mfma_f32_16x16x32_bf16 v[56:59], v[108:111], v[238:241], v[56:59]
	ds_read_b128 v[204:207], v226 offset:59392
	s_add_u32 m0, s1, 28672
	s_nop 0
	global_load_lds_dwordx4 v224, s[86:87]
	s_add_u32 s86, s86, 128
	s_addc_u32 s87, s87, 0
	s_waitcnt lgkmcnt(6)
	v_mfma_f32_16x16x32_bf16 v[28:31], v[100:103], v[242:245], v[28:31]
	v_mfma_f32_16x16x32_bf16 v[60:63], v[108:111], v[242:245], v[60:63]
	s_waitcnt vmcnt(12)
	ds_read_b128 v[208:211], v226 offset:61440
	s_waitcnt lgkmcnt(6)
	v_mfma_f32_16x16x32_bf16 v[0:3], v[64:67], v[112:115], v[0:3]
	v_mfma_f32_16x16x32_bf16 v[32:35], v[72:75], v[112:115], v[32:35]
	ds_read_b128 v[212:215], v226 offset:63488
	s_waitcnt lgkmcnt(6)
	v_mfma_f32_16x16x32_bf16 v[4:7], v[64:67], v[116:119], v[4:7]
	v_mfma_f32_16x16x32_bf16 v[36:39], v[72:75], v[116:119], v[36:39]
	ds_read_b128 v[230:233], v228 offset:49152
	s_waitcnt lgkmcnt(6)
	v_mfma_f32_16x16x32_bf16 v[8:11], v[64:67], v[120:123], v[8:11]
	v_mfma_f32_16x16x32_bf16 v[40:43], v[72:75], v[120:123], v[40:43]
	ds_read_b128 v[234:237], v228 offset:51200
	s_waitcnt lgkmcnt(6)
	v_mfma_f32_16x16x32_bf16 v[12:15], v[64:67], v[124:127], v[12:15]
	v_mfma_f32_16x16x32_bf16 v[44:47], v[72:75], v[124:127], v[44:47]
	ds_read_b128 v[238:241], v228 offset:53248
	s_waitcnt lgkmcnt(6)
	v_mfma_f32_16x16x32_bf16 v[16:19], v[64:67], v[200:203], v[16:19]
	v_mfma_f32_16x16x32_bf16 v[48:51], v[72:75], v[200:203], v[48:51]
	ds_read_b128 v[242:245], v228 offset:55296
	s_waitcnt lgkmcnt(6)
	v_mfma_f32_16x16x32_bf16 v[20:23], v[64:67], v[204:207], v[20:23]
	v_mfma_f32_16x16x32_bf16 v[52:55], v[72:75], v[204:207], v[52:55]
	ds_read_b128 v[112:115], v228 offset:57344
	s_waitcnt lgkmcnt(6)
	v_mfma_f32_16x16x32_bf16 v[24:27], v[64:67], v[208:211], v[24:27]
	v_mfma_f32_16x16x32_bf16 v[56:59], v[72:75], v[208:211], v[56:59]
	ds_read_b128 v[116:119], v228 offset:59392
	s_waitcnt lgkmcnt(6)
	v_mfma_f32_16x16x32_bf16 v[28:31], v[64:67], v[212:215], v[28:31]
	v_mfma_f32_16x16x32_bf16 v[60:63], v[72:75], v[212:215], v[60:63]
	s_waitcnt vmcnt(8)
	s_barrier
	ds_read_b128 v[120:123], v228 offset:61440
	global_load_dwordx4 v[96:99], v142, s[84:85] offset:0
	s_waitcnt lgkmcnt(6)
	v_mfma_f32_16x16x32_bf16 v[0:3], v[68:71], v[230:233], v[0:3]
	v_mfma_f32_16x16x32_bf16 v[32:35], v[76:79], v[230:233], v[32:35]
	ds_read_b128 v[124:127], v228 offset:63488
	global_load_dwordx4 v[100:103], v142, s[84:85] offset:1024
	s_waitcnt lgkmcnt(6)
	v_mfma_f32_16x16x32_bf16 v[4:7], v[68:71], v[234:237], v[4:7]
	v_mfma_f32_16x16x32_bf16 v[36:39], v[76:79], v[234:237], v[36:39]
	ds_read_b128 v[200:203], v226 offset:0
	global_load_dwordx4 v[104:107], v216, s[84:85] offset:0
	s_waitcnt lgkmcnt(6)
	v_mfma_f32_16x16x32_bf16 v[8:11], v[68:71], v[238:241], v[8:11]
	v_mfma_f32_16x16x32_bf16 v[40:43], v[76:79], v[238:241], v[40:43]
	ds_read_b128 v[204:207], v226 offset:2048
	global_load_dwordx4 v[108:111], v216, s[84:85] offset:1024
	s_add_u32 s84, s84, 0x800
	s_addc_u32 s85, s85, 0
	s_waitcnt lgkmcnt(6)
	v_mfma_f32_16x16x32_bf16 v[12:15], v[68:71], v[242:245], v[12:15]
	v_mfma_f32_16x16x32_bf16 v[44:47], v[76:79], v[242:245], v[44:47]
	ds_read_b128 v[208:211], v226 offset:4096
	s_add_u32 m0, s1, 32768
	s_nop 0
	global_load_lds_dwordx4 v218, s[86:87]
	s_waitcnt lgkmcnt(6)
	v_mfma_f32_16x16x32_bf16 v[16:19], v[68:71], v[112:115], v[16:19]
	v_mfma_f32_16x16x32_bf16 v[48:51], v[76:79], v[112:115], v[48:51]
	ds_read_b128 v[212:215], v226 offset:6144
	s_add_u32 m0, s1, 36864
	s_nop 0
	global_load_lds_dwordx4 v220, s[86:87]
	s_waitcnt lgkmcnt(6)
	v_mfma_f32_16x16x32_bf16 v[20:23], v[68:71], v[116:119], v[20:23]
	v_mfma_f32_16x16x32_bf16 v[52:55], v[76:79], v[116:119], v[52:55]
	ds_read_b128 v[230:233], v226 offset:8192
	s_add_u32 m0, s1, 40960
	s_nop 0
	global_load_lds_dwordx4 v222, s[86:87]
	s_waitcnt lgkmcnt(6)
	v_mfma_f32_16x16x32_bf16 v[24:27], v[68:71], v[120:123], v[24:27]
	v_mfma_f32_16x16x32_bf16 v[56:59], v[76:79], v[120:123], v[56:59]
	ds_read_b128 v[234:237], v226 offset:10240
	s_add_u32 m0, s1, 45056
	s_nop 0
	global_load_lds_dwordx4 v224, s[86:87]
	s_add_u32 s86, s86, 128
	s_addc_u32 s87, s87, 0
	s_waitcnt lgkmcnt(6)
	v_mfma_f32_16x16x32_bf16 v[28:31], v[68:71], v[124:127], v[28:31]
	v_mfma_f32_16x16x32_bf16 v[60:63], v[76:79], v[124:127], v[60:63]
	s_waitcnt vmcnt(12)
	ds_read_b128 v[238:241], v226 offset:12288
	s_waitcnt lgkmcnt(6)
	v_mfma_f32_16x16x32_bf16 v[0:3], v[80:83], v[200:203], v[0:3]
	v_mfma_f32_16x16x32_bf16 v[32:35], v[88:91], v[200:203], v[32:35]
	ds_read_b128 v[242:245], v226 offset:14336
	s_waitcnt lgkmcnt(6)
	v_mfma_f32_16x16x32_bf16 v[4:7], v[80:83], v[204:207], v[4:7]
	v_mfma_f32_16x16x32_bf16 v[36:39], v[88:91], v[204:207], v[36:39]
	ds_read_b128 v[112:115], v228 offset:0
	s_waitcnt lgkmcnt(6)
	v_mfma_f32_16x16x32_bf16 v[8:11], v[80:83], v[208:211], v[8:11]
	v_mfma_f32_16x16x32_bf16 v[40:43], v[88:91], v[208:211], v[40:43]
	ds_read_b128 v[116:119], v228 offset:2048
	s_waitcnt lgkmcnt(6)
	v_mfma_f32_16x16x32_bf16 v[12:15], v[80:83], v[212:215], v[12:15]
	v_mfma_f32_16x16x32_bf16 v[44:47], v[88:91], v[212:215], v[44:47]
	ds_read_b128 v[120:123], v228 offset:4096
	s_waitcnt lgkmcnt(6)
	v_mfma_f32_16x16x32_bf16 v[16:19], v[80:83], v[230:233], v[16:19]
	v_mfma_f32_16x16x32_bf16 v[48:51], v[88:91], v[230:233], v[48:51]
	ds_read_b128 v[124:127], v228 offset:6144
	s_waitcnt lgkmcnt(6)
	v_mfma_f32_16x16x32_bf16 v[20:23], v[80:83], v[234:237], v[20:23]
	v_mfma_f32_16x16x32_bf16 v[52:55], v[88:91], v[234:237], v[52:55]
	ds_read_b128 v[200:203], v228 offset:8192
	s_waitcnt lgkmcnt(6)
	v_mfma_f32_16x16x32_bf16 v[24:27], v[80:83], v[238:241], v[24:27]
	v_mfma_f32_16x16x32_bf16 v[56:59], v[88:91], v[238:241], v[56:59]
	ds_read_b128 v[204:207], v228 offset:10240
	s_waitcnt lgkmcnt(6)
	v_mfma_f32_16x16x32_bf16 v[28:31], v[80:83], v[242:245], v[28:31]
	v_mfma_f32_16x16x32_bf16 v[60:63], v[88:91], v[242:245], v[60:63]
	s_waitcnt vmcnt(8)
	s_barrier
	ds_read_b128 v[208:211], v228 offset:12288
	global_load_dwordx4 v[64:67], v142, s[84:85] offset:0
	s_waitcnt lgkmcnt(6)
	v_mfma_f32_16x16x32_bf16 v[0:3], v[84:87], v[112:115], v[0:3]
	v_mfma_f32_16x16x32_bf16 v[32:35], v[92:95], v[112:115], v[32:35]
	ds_read_b128 v[212:215], v228 offset:14336
	global_load_dwordx4 v[68:71], v142, s[84:85] offset:1024
	s_waitcnt lgkmcnt(6)
	v_mfma_f32_16x16x32_bf16 v[4:7], v[84:87], v[116:119], v[4:7]
	v_mfma_f32_16x16x32_bf16 v[36:39], v[92:95], v[116:119], v[36:39]
	ds_read_b128 v[230:233], v226 offset:16384
	global_load_dwordx4 v[72:75], v216, s[84:85] offset:0
	s_waitcnt lgkmcnt(6)
	v_mfma_f32_16x16x32_bf16 v[8:11], v[84:87], v[120:123], v[8:11]
	v_mfma_f32_16x16x32_bf16 v[40:43], v[92:95], v[120:123], v[40:43]
	ds_read_b128 v[234:237], v226 offset:18432
	global_load_dwordx4 v[76:79], v216, s[84:85] offset:1024
	s_add_u32 s84, s84, 0x800
	s_addc_u32 s85, s85, 0
	s_waitcnt lgkmcnt(6)
	v_mfma_f32_16x16x32_bf16 v[12:15], v[84:87], v[124:127], v[12:15]
	v_mfma_f32_16x16x32_bf16 v[44:47], v[92:95], v[124:127], v[44:47]
	ds_read_b128 v[238:241], v226 offset:20480
	s_add_u32 m0, s1, 49152
	s_nop 0
	global_load_lds_dwordx4 v218, s[86:87]
	s_waitcnt lgkmcnt(6)
	v_mfma_f32_16x16x32_bf16 v[16:19], v[84:87], v[200:203], v[16:19]
	v_mfma_f32_16x16x32_bf16 v[48:51], v[92:95], v[200:203], v[48:51]
	ds_read_b128 v[242:245], v226 offset:22528
	s_add_u32 m0, s1, 53248
	s_nop 0
	global_load_lds_dwordx4 v220, s[86:87]
	s_waitcnt lgkmcnt(6)
	v_mfma_f32_16x16x32_bf16 v[20:23], v[84:87], v[204:207], v[20:23]
	v_mfma_f32_16x16x32_bf16 v[52:55], v[92:95], v[204:207], v[52:55]
	ds_read_b128 v[112:115], v226 offset:24576
	s_add_u32 m0, s1, 57344
	s_nop 0
	global_load_lds_dwordx4 v222, s[86:87]
	s_waitcnt lgkmcnt(6)
	v_mfma_f32_16x16x32_bf16 v[24:27], v[84:87], v[208:211], v[24:27]
	v_mfma_f32_16x16x32_bf16 v[56:59], v[92:95], v[208:211], v[56:59]
	ds_read_b128 v[116:119], v226 offset:26624
	s_add_u32 m0, s1, 61440
	s_nop 0
	global_load_lds_dwordx4 v224, s[86:87]
	s_add_u32 s86, s86, 128
	s_addc_u32 s87, s87, 0
	s_waitcnt lgkmcnt(6)
	v_mfma_f32_16x16x32_bf16 v[28:31], v[84:87], v[212:215], v[28:31]
	v_mfma_f32_16x16x32_bf16 v[60:63], v[92:95], v[212:215], v[60:63]
	s_waitcnt vmcnt(12)
	ds_read_b128 v[120:123], v226 offset:28672
	s_waitcnt lgkmcnt(6)
	v_mfma_f32_16x16x32_bf16 v[0:3], v[96:99], v[230:233], v[0:3]
	v_mfma_f32_16x16x32_bf16 v[32:35], v[104:107], v[230:233], v[32:35]
	ds_read_b128 v[124:127], v226 offset:30720
	s_waitcnt lgkmcnt(6)
	v_mfma_f32_16x16x32_bf16 v[4:7], v[96:99], v[234:237], v[4:7]
	v_mfma_f32_16x16x32_bf16 v[36:39], v[104:107], v[234:237], v[36:39]
	ds_read_b128 v[200:203], v228 offset:16384
	s_waitcnt lgkmcnt(6)
	v_mfma_f32_16x16x32_bf16 v[8:11], v[96:99], v[238:241], v[8:11]
	v_mfma_f32_16x16x32_bf16 v[40:43], v[104:107], v[238:241], v[40:43]
	ds_read_b128 v[204:207], v228 offset:18432
	s_waitcnt lgkmcnt(6)
	v_mfma_f32_16x16x32_bf16 v[12:15], v[96:99], v[242:245], v[12:15]
	v_mfma_f32_16x16x32_bf16 v[44:47], v[104:107], v[242:245], v[44:47]
	ds_read_b128 v[208:211], v228 offset:20480
	s_waitcnt lgkmcnt(6)
	v_mfma_f32_16x16x32_bf16 v[16:19], v[96:99], v[112:115], v[16:19]
	v_mfma_f32_16x16x32_bf16 v[48:51], v[104:107], v[112:115], v[48:51]
	ds_read_b128 v[212:215], v228 offset:22528
	s_waitcnt lgkmcnt(6)
	v_mfma_f32_16x16x32_bf16 v[20:23], v[96:99], v[116:119], v[20:23]
	v_mfma_f32_16x16x32_bf16 v[52:55], v[104:107], v[116:119], v[52:55]
	ds_read_b128 v[230:233], v228 offset:24576
	s_waitcnt lgkmcnt(6)
	v_mfma_f32_16x16x32_bf16 v[24:27], v[96:99], v[120:123], v[24:27]
	v_mfma_f32_16x16x32_bf16 v[56:59], v[104:107], v[120:123], v[56:59]
	ds_read_b128 v[234:237], v228 offset:26624
	s_waitcnt lgkmcnt(6)
	v_mfma_f32_16x16x32_bf16 v[28:31], v[96:99], v[124:127], v[28:31]
	v_mfma_f32_16x16x32_bf16 v[60:63], v[104:107], v[124:127], v[60:63]
	s_waitcnt vmcnt(8)
	s_barrier
	ds_read_b128 v[238:241], v228 offset:28672
	global_load_dwordx4 v[80:83], v142, s[84:85] offset:0
	s_waitcnt lgkmcnt(6)
	v_mfma_f32_16x16x32_bf16 v[0:3], v[100:103], v[200:203], v[0:3]
	v_mfma_f32_16x16x32_bf16 v[32:35], v[108:111], v[200:203], v[32:35]
	ds_read_b128 v[242:245], v228 offset:30720
	global_load_dwordx4 v[84:87], v142, s[84:85] offset:1024
	s_waitcnt lgkmcnt(6)
	v_mfma_f32_16x16x32_bf16 v[4:7], v[100:103], v[204:207], v[4:7]
	v_mfma_f32_16x16x32_bf16 v[36:39], v[108:111], v[204:207], v[36:39]
	ds_read_b128 v[112:115], v226 offset:32768
	global_load_dwordx4 v[88:91], v216, s[84:85] offset:0
	s_waitcnt lgkmcnt(6)
	v_mfma_f32_16x16x32_bf16 v[8:11], v[100:103], v[208:211], v[8:11]
	v_mfma_f32_16x16x32_bf16 v[40:43], v[108:111], v[208:211], v[40:43]
	ds_read_b128 v[116:119], v226 offset:34816
	global_load_dwordx4 v[92:95], v216, s[84:85] offset:1024
	s_add_u32 s84, s84, 0x800
	s_addc_u32 s85, s85, 0
	s_waitcnt lgkmcnt(6)
	v_mfma_f32_16x16x32_bf16 v[12:15], v[100:103], v[212:215], v[12:15]
	v_mfma_f32_16x16x32_bf16 v[44:47], v[108:111], v[212:215], v[44:47]
	ds_read_b128 v[120:123], v226 offset:36864
	s_add_u32 m0, s1, 0
	s_nop 0
	global_load_lds_dwordx4 v218, s[86:87]
	s_waitcnt lgkmcnt(6)
	v_mfma_f32_16x16x32_bf16 v[16:19], v[100:103], v[230:233], v[16:19]
	v_mfma_f32_16x16x32_bf16 v[48:51], v[108:111], v[230:233], v[48:51]
	ds_read_b128 v[124:127], v226 offset:38912
	s_add_u32 m0, s1, 4096
	s_nop 0
	global_load_lds_dwordx4 v220, s[86:87]
	s_waitcnt lgkmcnt(6)
	v_mfma_f32_16x16x32_bf16 v[20:23], v[100:103], v[234:237], v[20:23]
	v_mfma_f32_16x16x32_bf16 v[52:55], v[108:111], v[234:237], v[52:55]
	ds_read_b128 v[200:203], v226 offset:40960
	s_add_u32 m0, s1, 8192
	s_nop 0
	global_load_lds_dwordx4 v222, s[86:87]
	s_waitcnt lgkmcnt(6)
	v_mfma_f32_16x16x32_bf16 v[24:27], v[100:103], v[238:241], v[24:27]
	v_mfma_f32_16x16x32_bf16 v[56:59], v[108:111], v[238:241], v[56:59]
	ds_read_b128 v[204:207], v226 offset:43008
	s_add_u32 m0, s1, 12288
	s_nop 0
	global_load_lds_dwordx4 v224, s[86:87]
	s_add_u32 s86, s86, 128
	s_addc_u32 s87, s87, 0
	s_waitcnt lgkmcnt(6)
	v_mfma_f32_16x16x32_bf16 v[28:31], v[100:103], v[242:245], v[28:31]
	v_mfma_f32_16x16x32_bf16 v[60:63], v[108:111], v[242:245], v[60:63]
	s_waitcnt vmcnt(12)
	ds_read_b128 v[208:211], v226 offset:45056
	s_waitcnt lgkmcnt(6)
	v_mfma_f32_16x16x32_bf16 v[0:3], v[64:67], v[112:115], v[0:3]
	v_mfma_f32_16x16x32_bf16 v[32:35], v[72:75], v[112:115], v[32:35]
	ds_read_b128 v[212:215], v226 offset:47104
	s_waitcnt lgkmcnt(6)
	v_mfma_f32_16x16x32_bf16 v[4:7], v[64:67], v[116:119], v[4:7]
	v_mfma_f32_16x16x32_bf16 v[36:39], v[72:75], v[116:119], v[36:39]
	ds_read_b128 v[230:233], v228 offset:32768
	s_waitcnt lgkmcnt(6)
	v_mfma_f32_16x16x32_bf16 v[8:11], v[64:67], v[120:123], v[8:11]
	v_mfma_f32_16x16x32_bf16 v[40:43], v[72:75], v[120:123], v[40:43]
	ds_read_b128 v[234:237], v228 offset:34816
	s_waitcnt lgkmcnt(6)
	v_mfma_f32_16x16x32_bf16 v[12:15], v[64:67], v[124:127], v[12:15]
	v_mfma_f32_16x16x32_bf16 v[44:47], v[72:75], v[124:127], v[44:47]
	ds_read_b128 v[238:241], v228 offset:36864
	s_waitcnt lgkmcnt(6)
	v_mfma_f32_16x16x32_bf16 v[16:19], v[64:67], v[200:203], v[16:19]
	v_mfma_f32_16x16x32_bf16 v[48:51], v[72:75], v[200:203], v[48:51]
	ds_read_b128 v[242:245], v228 offset:38912
	s_waitcnt lgkmcnt(6)
	v_mfma_f32_16x16x32_bf16 v[20:23], v[64:67], v[204:207], v[20:23]
	v_mfma_f32_16x16x32_bf16 v[52:55], v[72:75], v[204:207], v[52:55]
	ds_read_b128 v[112:115], v228 offset:40960
	s_waitcnt lgkmcnt(6)
	v_mfma_f32_16x16x32_bf16 v[24:27], v[64:67], v[208:211], v[24:27]
	v_mfma_f32_16x16x32_bf16 v[56:59], v[72:75], v[208:211], v[56:59]
	ds_read_b128 v[116:119], v228 offset:43008
	s_waitcnt lgkmcnt(6)
	v_mfma_f32_16x16x32_bf16 v[28:31], v[64:67], v[212:215], v[28:31]
	v_mfma_f32_16x16x32_bf16 v[60:63], v[72:75], v[212:215], v[60:63]
	s_waitcnt vmcnt(8)
	s_barrier
	ds_read_b128 v[120:123], v228 offset:45056
	global_load_dwordx4 v[96:99], v142, s[84:85] offset:0
	s_waitcnt lgkmcnt(6)
	v_mfma_f32_16x16x32_bf16 v[0:3], v[68:71], v[230:233], v[0:3]
	v_mfma_f32_16x16x32_bf16 v[32:35], v[76:79], v[230:233], v[32:35]
	ds_read_b128 v[124:127], v228 offset:47104
	global_load_dwordx4 v[100:103], v142, s[84:85] offset:1024
	s_waitcnt lgkmcnt(6)
	v_mfma_f32_16x16x32_bf16 v[4:7], v[68:71], v[234:237], v[4:7]
	v_mfma_f32_16x16x32_bf16 v[36:39], v[76:79], v[234:237], v[36:39]
	ds_read_b128 v[200:203], v226 offset:49152
	global_load_dwordx4 v[104:107], v216, s[84:85] offset:0
	s_waitcnt lgkmcnt(6)
	v_mfma_f32_16x16x32_bf16 v[8:11], v[68:71], v[238:241], v[8:11]
	v_mfma_f32_16x16x32_bf16 v[40:43], v[76:79], v[238:241], v[40:43]
	ds_read_b128 v[204:207], v226 offset:51200
	global_load_dwordx4 v[108:111], v216, s[84:85] offset:1024
	s_add_u32 s84, s84, 0x800
	s_addc_u32 s85, s85, 0
	s_waitcnt lgkmcnt(6)
	v_mfma_f32_16x16x32_bf16 v[12:15], v[68:71], v[242:245], v[12:15]
	v_mfma_f32_16x16x32_bf16 v[44:47], v[76:79], v[242:245], v[44:47]
	ds_read_b128 v[208:211], v226 offset:53248
	s_add_u32 m0, s1, 16384
	s_nop 0
	global_load_lds_dwordx4 v218, s[86:87]
	s_waitcnt lgkmcnt(6)
	v_mfma_f32_16x16x32_bf16 v[16:19], v[68:71], v[112:115], v[16:19]
	v_mfma_f32_16x16x32_bf16 v[48:51], v[76:79], v[112:115], v[48:51]
	ds_read_b128 v[212:215], v226 offset:55296
	s_add_u32 m0, s1, 20480
	s_nop 0
	global_load_lds_dwordx4 v220, s[86:87]
	s_waitcnt lgkmcnt(6)
	v_mfma_f32_16x16x32_bf16 v[20:23], v[68:71], v[116:119], v[20:23]
	v_mfma_f32_16x16x32_bf16 v[52:55], v[76:79], v[116:119], v[52:55]
	ds_read_b128 v[230:233], v226 offset:57344
	s_add_u32 m0, s1, 24576
	s_nop 0
	global_load_lds_dwordx4 v222, s[86:87]
	s_waitcnt lgkmcnt(6)
	v_mfma_f32_16x16x32_bf16 v[24:27], v[68:71], v[120:123], v[24:27]
	v_mfma_f32_16x16x32_bf16 v[56:59], v[76:79], v[120:123], v[56:59]
	ds_read_b128 v[234:237], v226 offset:59392
	s_add_u32 m0, s1, 28672
	s_nop 0
	global_load_lds_dwordx4 v224, s[86:87]
	s_add_u32 s86, s86, 128
	s_addc_u32 s87, s87, 0
	s_waitcnt lgkmcnt(6)
	v_mfma_f32_16x16x32_bf16 v[28:31], v[68:71], v[124:127], v[28:31]
	v_mfma_f32_16x16x32_bf16 v[60:63], v[76:79], v[124:127], v[60:63]
	s_waitcnt vmcnt(12)
	ds_read_b128 v[238:241], v226 offset:61440
	s_waitcnt lgkmcnt(6)
	v_mfma_f32_16x16x32_bf16 v[0:3], v[80:83], v[200:203], v[0:3]
	v_mfma_f32_16x16x32_bf16 v[32:35], v[88:91], v[200:203], v[32:35]
	ds_read_b128 v[242:245], v226 offset:63488
	s_waitcnt lgkmcnt(6)
	v_mfma_f32_16x16x32_bf16 v[4:7], v[80:83], v[204:207], v[4:7]
	v_mfma_f32_16x16x32_bf16 v[36:39], v[88:91], v[204:207], v[36:39]
	ds_read_b128 v[112:115], v228 offset:49152
	s_waitcnt lgkmcnt(6)
	v_mfma_f32_16x16x32_bf16 v[8:11], v[80:83], v[208:211], v[8:11]
	v_mfma_f32_16x16x32_bf16 v[40:43], v[88:91], v[208:211], v[40:43]
	ds_read_b128 v[116:119], v228 offset:51200
	s_waitcnt lgkmcnt(6)
	v_mfma_f32_16x16x32_bf16 v[12:15], v[80:83], v[212:215], v[12:15]
	v_mfma_f32_16x16x32_bf16 v[44:47], v[88:91], v[212:215], v[44:47]
	ds_read_b128 v[120:123], v228 offset:53248
	s_waitcnt lgkmcnt(6)
	v_mfma_f32_16x16x32_bf16 v[16:19], v[80:83], v[230:233], v[16:19]
	v_mfma_f32_16x16x32_bf16 v[48:51], v[88:91], v[230:233], v[48:51]
	ds_read_b128 v[124:127], v228 offset:55296
	s_waitcnt lgkmcnt(6)
	v_mfma_f32_16x16x32_bf16 v[20:23], v[80:83], v[234:237], v[20:23]
	v_mfma_f32_16x16x32_bf16 v[52:55], v[88:91], v[234:237], v[52:55]
	ds_read_b128 v[200:203], v228 offset:57344
	s_waitcnt lgkmcnt(6)
	v_mfma_f32_16x16x32_bf16 v[24:27], v[80:83], v[238:241], v[24:27]
	v_mfma_f32_16x16x32_bf16 v[56:59], v[88:91], v[238:241], v[56:59]
	ds_read_b128 v[204:207], v228 offset:59392
	s_waitcnt lgkmcnt(6)
	v_mfma_f32_16x16x32_bf16 v[28:31], v[80:83], v[242:245], v[28:31]
	v_mfma_f32_16x16x32_bf16 v[60:63], v[88:91], v[242:245], v[60:63]
	s_waitcnt vmcnt(8)
	s_barrier
	ds_read_b128 v[208:211], v228 offset:61440
	global_load_dwordx4 v[64:67], v142, s[84:85] offset:0
	s_waitcnt lgkmcnt(6)
	v_mfma_f32_16x16x32_bf16 v[0:3], v[84:87], v[112:115], v[0:3]
	v_mfma_f32_16x16x32_bf16 v[32:35], v[92:95], v[112:115], v[32:35]
	ds_read_b128 v[212:215], v228 offset:63488
	global_load_dwordx4 v[68:71], v142, s[84:85] offset:1024
	s_waitcnt lgkmcnt(6)
	v_mfma_f32_16x16x32_bf16 v[4:7], v[84:87], v[116:119], v[4:7]
	v_mfma_f32_16x16x32_bf16 v[36:39], v[92:95], v[116:119], v[36:39]
	ds_read_b128 v[230:233], v226 offset:0
	global_load_dwordx4 v[72:75], v216, s[84:85] offset:0
	s_waitcnt lgkmcnt(6)
	v_mfma_f32_16x16x32_bf16 v[8:11], v[84:87], v[120:123], v[8:11]
	v_mfma_f32_16x16x32_bf16 v[40:43], v[92:95], v[120:123], v[40:43]
	ds_read_b128 v[234:237], v226 offset:2048
	global_load_dwordx4 v[76:79], v216, s[84:85] offset:1024
	s_add_u32 s84, s84, 0x800
	s_addc_u32 s85, s85, 0
	s_waitcnt lgkmcnt(6)
	v_mfma_f32_16x16x32_bf16 v[12:15], v[84:87], v[124:127], v[12:15]
	v_mfma_f32_16x16x32_bf16 v[44:47], v[92:95], v[124:127], v[44:47]
	ds_read_b128 v[238:241], v226 offset:4096
	s_add_u32 m0, s1, 32768
	s_nop 0
	global_load_lds_dwordx4 v218, s[86:87]
	s_waitcnt lgkmcnt(6)
	v_mfma_f32_16x16x32_bf16 v[16:19], v[84:87], v[200:203], v[16:19]
	v_mfma_f32_16x16x32_bf16 v[48:51], v[92:95], v[200:203], v[48:51]
	ds_read_b128 v[242:245], v226 offset:6144
	s_add_u32 m0, s1, 36864
	s_nop 0
	global_load_lds_dwordx4 v220, s[86:87]
	s_waitcnt lgkmcnt(6)
	v_mfma_f32_16x16x32_bf16 v[20:23], v[84:87], v[204:207], v[20:23]
	v_mfma_f32_16x16x32_bf16 v[52:55], v[92:95], v[204:207], v[52:55]
	ds_read_b128 v[112:115], v226 offset:8192
	s_add_u32 m0, s1, 40960
	s_nop 0
	global_load_lds_dwordx4 v222, s[86:87]
	s_waitcnt lgkmcnt(6)
	v_mfma_f32_16x16x32_bf16 v[24:27], v[84:87], v[208:211], v[24:27]
	v_mfma_f32_16x16x32_bf16 v[56:59], v[92:95], v[208:211], v[56:59]
	ds_read_b128 v[116:119], v226 offset:10240
	s_add_u32 m0, s1, 45056
	s_nop 0
	global_load_lds_dwordx4 v224, s[86:87]
	s_add_u32 s86, s86, 128
	s_addc_u32 s87, s87, 0
	s_waitcnt lgkmcnt(6)
	v_mfma_f32_16x16x32_bf16 v[28:31], v[84:87], v[212:215], v[28:31]
	v_mfma_f32_16x16x32_bf16 v[60:63], v[92:95], v[212:215], v[60:63]
	s_waitcnt vmcnt(12)
	ds_read_b128 v[120:123], v226 offset:12288
	s_waitcnt lgkmcnt(6)
	v_mfma_f32_16x16x32_bf16 v[0:3], v[96:99], v[230:233], v[0:3]
	v_mfma_f32_16x16x32_bf16 v[32:35], v[104:107], v[230:233], v[32:35]
	ds_read_b128 v[124:127], v226 offset:14336
	s_waitcnt lgkmcnt(6)
	v_mfma_f32_16x16x32_bf16 v[4:7], v[96:99], v[234:237], v[4:7]
	v_mfma_f32_16x16x32_bf16 v[36:39], v[104:107], v[234:237], v[36:39]
	ds_read_b128 v[200:203], v228 offset:0
	s_waitcnt lgkmcnt(6)
	v_mfma_f32_16x16x32_bf16 v[8:11], v[96:99], v[238:241], v[8:11]
	v_mfma_f32_16x16x32_bf16 v[40:43], v[104:107], v[238:241], v[40:43]
	ds_read_b128 v[204:207], v228 offset:2048
	s_waitcnt lgkmcnt(6)
	v_mfma_f32_16x16x32_bf16 v[12:15], v[96:99], v[242:245], v[12:15]
	v_mfma_f32_16x16x32_bf16 v[44:47], v[104:107], v[242:245], v[44:47]
	ds_read_b128 v[208:211], v228 offset:4096
	s_waitcnt lgkmcnt(6)
	v_mfma_f32_16x16x32_bf16 v[16:19], v[96:99], v[112:115], v[16:19]
	v_mfma_f32_16x16x32_bf16 v[48:51], v[104:107], v[112:115], v[48:51]
	ds_read_b128 v[212:215], v228 offset:6144
	s_waitcnt lgkmcnt(6)
	v_mfma_f32_16x16x32_bf16 v[20:23], v[96:99], v[116:119], v[20:23]
	v_mfma_f32_16x16x32_bf16 v[52:55], v[104:107], v[116:119], v[52:55]
	ds_read_b128 v[230:233], v228 offset:8192
	s_waitcnt lgkmcnt(6)
	v_mfma_f32_16x16x32_bf16 v[24:27], v[96:99], v[120:123], v[24:27]
	v_mfma_f32_16x16x32_bf16 v[56:59], v[104:107], v[120:123], v[56:59]
	ds_read_b128 v[234:237], v228 offset:10240
	s_waitcnt lgkmcnt(6)
	v_mfma_f32_16x16x32_bf16 v[28:31], v[96:99], v[124:127], v[28:31]
	v_mfma_f32_16x16x32_bf16 v[60:63], v[104:107], v[124:127], v[60:63]
	s_waitcnt vmcnt(8)
	s_barrier
	ds_read_b128 v[238:241], v228 offset:12288
	global_load_dwordx4 v[80:83], v142, s[84:85] offset:0
	s_waitcnt lgkmcnt(6)
	v_mfma_f32_16x16x32_bf16 v[0:3], v[100:103], v[200:203], v[0:3]
	v_mfma_f32_16x16x32_bf16 v[32:35], v[108:111], v[200:203], v[32:35]
	ds_read_b128 v[242:245], v228 offset:14336
	global_load_dwordx4 v[84:87], v142, s[84:85] offset:1024
	s_waitcnt lgkmcnt(6)
	v_mfma_f32_16x16x32_bf16 v[4:7], v[100:103], v[204:207], v[4:7]
	v_mfma_f32_16x16x32_bf16 v[36:39], v[108:111], v[204:207], v[36:39]
	ds_read_b128 v[112:115], v226 offset:16384
	global_load_dwordx4 v[88:91], v216, s[84:85] offset:0
	s_waitcnt lgkmcnt(6)
	v_mfma_f32_16x16x32_bf16 v[8:11], v[100:103], v[208:211], v[8:11]
	v_mfma_f32_16x16x32_bf16 v[40:43], v[108:111], v[208:211], v[40:43]
	ds_read_b128 v[116:119], v226 offset:18432
	global_load_dwordx4 v[92:95], v216, s[84:85] offset:1024
	s_add_u32 s84, s84, 0x800
	s_addc_u32 s85, s85, 0
	s_waitcnt lgkmcnt(6)
	v_mfma_f32_16x16x32_bf16 v[12:15], v[100:103], v[212:215], v[12:15]
	v_mfma_f32_16x16x32_bf16 v[44:47], v[108:111], v[212:215], v[44:47]
	ds_read_b128 v[120:123], v226 offset:20480
	s_add_u32 m0, s1, 49152
	s_nop 0
	global_load_lds_dwordx4 v218, s[86:87]
	s_waitcnt lgkmcnt(6)
	v_mfma_f32_16x16x32_bf16 v[16:19], v[100:103], v[230:233], v[16:19]
	v_mfma_f32_16x16x32_bf16 v[48:51], v[108:111], v[230:233], v[48:51]
	ds_read_b128 v[124:127], v226 offset:22528
	s_add_u32 m0, s1, 53248
	s_nop 0
	global_load_lds_dwordx4 v220, s[86:87]
	s_waitcnt lgkmcnt(6)
	v_mfma_f32_16x16x32_bf16 v[20:23], v[100:103], v[234:237], v[20:23]
	v_mfma_f32_16x16x32_bf16 v[52:55], v[108:111], v[234:237], v[52:55]
	ds_read_b128 v[200:203], v226 offset:24576
	s_add_u32 m0, s1, 57344
	s_nop 0
	global_load_lds_dwordx4 v222, s[86:87]
	s_waitcnt lgkmcnt(6)
	v_mfma_f32_16x16x32_bf16 v[24:27], v[100:103], v[238:241], v[24:27]
	v_mfma_f32_16x16x32_bf16 v[56:59], v[108:111], v[238:241], v[56:59]
	ds_read_b128 v[204:207], v226 offset:26624
	s_add_u32 m0, s1, 61440
	s_nop 0
	global_load_lds_dwordx4 v224, s[86:87]
	s_add_u32 s86, s86, 128
	s_addc_u32 s87, s87, 0
	s_waitcnt lgkmcnt(6)
	v_mfma_f32_16x16x32_bf16 v[28:31], v[100:103], v[242:245], v[28:31]
	v_mfma_f32_16x16x32_bf16 v[60:63], v[108:111], v[242:245], v[60:63]
	s_waitcnt vmcnt(12)
	ds_read_b128 v[208:211], v226 offset:28672
	s_waitcnt lgkmcnt(6)
	v_mfma_f32_16x16x32_bf16 v[0:3], v[64:67], v[112:115], v[0:3]
	v_mfma_f32_16x16x32_bf16 v[32:35], v[72:75], v[112:115], v[32:35]
	ds_read_b128 v[212:215], v226 offset:30720
	s_waitcnt lgkmcnt(6)
	v_mfma_f32_16x16x32_bf16 v[4:7], v[64:67], v[116:119], v[4:7]
	v_mfma_f32_16x16x32_bf16 v[36:39], v[72:75], v[116:119], v[36:39]
	ds_read_b128 v[230:233], v228 offset:16384
	s_waitcnt lgkmcnt(6)
	v_mfma_f32_16x16x32_bf16 v[8:11], v[64:67], v[120:123], v[8:11]
	v_mfma_f32_16x16x32_bf16 v[40:43], v[72:75], v[120:123], v[40:43]
	ds_read_b128 v[234:237], v228 offset:18432
	s_waitcnt lgkmcnt(6)
	v_mfma_f32_16x16x32_bf16 v[12:15], v[64:67], v[124:127], v[12:15]
	v_mfma_f32_16x16x32_bf16 v[44:47], v[72:75], v[124:127], v[44:47]
	ds_read_b128 v[238:241], v228 offset:20480
	s_waitcnt lgkmcnt(6)
	v_mfma_f32_16x16x32_bf16 v[16:19], v[64:67], v[200:203], v[16:19]
	v_mfma_f32_16x16x32_bf16 v[48:51], v[72:75], v[200:203], v[48:51]
	ds_read_b128 v[242:245], v228 offset:22528
	s_waitcnt lgkmcnt(6)
	v_mfma_f32_16x16x32_bf16 v[20:23], v[64:67], v[204:207], v[20:23]
	v_mfma_f32_16x16x32_bf16 v[52:55], v[72:75], v[204:207], v[52:55]
	ds_read_b128 v[112:115], v228 offset:24576
	s_waitcnt lgkmcnt(6)
	v_mfma_f32_16x16x32_bf16 v[24:27], v[64:67], v[208:211], v[24:27]
	v_mfma_f32_16x16x32_bf16 v[56:59], v[72:75], v[208:211], v[56:59]
	ds_read_b128 v[116:119], v228 offset:26624
	s_waitcnt lgkmcnt(6)
	v_mfma_f32_16x16x32_bf16 v[28:31], v[64:67], v[212:215], v[28:31]
	v_mfma_f32_16x16x32_bf16 v[60:63], v[72:75], v[212:215], v[60:63]
	s_waitcnt vmcnt(8)
	s_barrier
	ds_read_b128 v[120:123], v228 offset:28672
	global_load_dwordx4 v[96:99], v142, s[84:85] offset:0
	s_waitcnt lgkmcnt(6)
	v_mfma_f32_16x16x32_bf16 v[0:3], v[68:71], v[230:233], v[0:3]
	v_mfma_f32_16x16x32_bf16 v[32:35], v[76:79], v[230:233], v[32:35]
	ds_read_b128 v[124:127], v228 offset:30720
	global_load_dwordx4 v[100:103], v142, s[84:85] offset:1024
	s_waitcnt lgkmcnt(6)
	v_mfma_f32_16x16x32_bf16 v[4:7], v[68:71], v[234:237], v[4:7]
	v_mfma_f32_16x16x32_bf16 v[36:39], v[76:79], v[234:237], v[36:39]
	ds_read_b128 v[200:203], v226 offset:32768
	global_load_dwordx4 v[104:107], v216, s[84:85] offset:0
	s_waitcnt lgkmcnt(6)
	v_mfma_f32_16x16x32_bf16 v[8:11], v[68:71], v[238:241], v[8:11]
	v_mfma_f32_16x16x32_bf16 v[40:43], v[76:79], v[238:241], v[40:43]
	ds_read_b128 v[204:207], v226 offset:34816
	global_load_dwordx4 v[108:111], v216, s[84:85] offset:1024
	s_add_u32 s84, s84, 0x800
	s_addc_u32 s85, s85, 0
	s_waitcnt lgkmcnt(6)
	v_mfma_f32_16x16x32_bf16 v[12:15], v[68:71], v[242:245], v[12:15]
	v_mfma_f32_16x16x32_bf16 v[44:47], v[76:79], v[242:245], v[44:47]
	ds_read_b128 v[208:211], v226 offset:36864
	s_add_u32 m0, s1, 0
	s_nop 0
	global_load_lds_dwordx4 v218, s[86:87]
	s_waitcnt lgkmcnt(6)
	v_mfma_f32_16x16x32_bf16 v[16:19], v[68:71], v[112:115], v[16:19]
	v_mfma_f32_16x16x32_bf16 v[48:51], v[76:79], v[112:115], v[48:51]
	ds_read_b128 v[212:215], v226 offset:38912
	s_add_u32 m0, s1, 4096
	s_nop 0
	global_load_lds_dwordx4 v220, s[86:87]
	s_waitcnt lgkmcnt(6)
	v_mfma_f32_16x16x32_bf16 v[20:23], v[68:71], v[116:119], v[20:23]
	v_mfma_f32_16x16x32_bf16 v[52:55], v[76:79], v[116:119], v[52:55]
	ds_read_b128 v[230:233], v226 offset:40960
	s_add_u32 m0, s1, 8192
	s_nop 0
	global_load_lds_dwordx4 v222, s[86:87]
	s_waitcnt lgkmcnt(6)
	v_mfma_f32_16x16x32_bf16 v[24:27], v[68:71], v[120:123], v[24:27]
	v_mfma_f32_16x16x32_bf16 v[56:59], v[76:79], v[120:123], v[56:59]
	ds_read_b128 v[234:237], v226 offset:43008
	s_add_u32 m0, s1, 12288
	s_nop 0
	global_load_lds_dwordx4 v224, s[86:87]
	s_add_u32 s86, s86, 128
	s_addc_u32 s87, s87, 0
	s_waitcnt lgkmcnt(6)
	v_mfma_f32_16x16x32_bf16 v[28:31], v[68:71], v[124:127], v[28:31]
	v_mfma_f32_16x16x32_bf16 v[60:63], v[76:79], v[124:127], v[60:63]
	s_waitcnt vmcnt(12)
	ds_read_b128 v[238:241], v226 offset:45056
	s_waitcnt lgkmcnt(6)
	v_mfma_f32_16x16x32_bf16 v[0:3], v[80:83], v[200:203], v[0:3]
	v_mfma_f32_16x16x32_bf16 v[32:35], v[88:91], v[200:203], v[32:35]
	ds_read_b128 v[242:245], v226 offset:47104
	s_waitcnt lgkmcnt(6)
	v_mfma_f32_16x16x32_bf16 v[4:7], v[80:83], v[204:207], v[4:7]
	v_mfma_f32_16x16x32_bf16 v[36:39], v[88:91], v[204:207], v[36:39]
	ds_read_b128 v[112:115], v228 offset:32768
	s_waitcnt lgkmcnt(6)
	v_mfma_f32_16x16x32_bf16 v[8:11], v[80:83], v[208:211], v[8:11]
	v_mfma_f32_16x16x32_bf16 v[40:43], v[88:91], v[208:211], v[40:43]
	ds_read_b128 v[116:119], v228 offset:34816
	s_waitcnt lgkmcnt(6)
	v_mfma_f32_16x16x32_bf16 v[12:15], v[80:83], v[212:215], v[12:15]
	v_mfma_f32_16x16x32_bf16 v[44:47], v[88:91], v[212:215], v[44:47]
	ds_read_b128 v[120:123], v228 offset:36864
	s_waitcnt lgkmcnt(6)
	v_mfma_f32_16x16x32_bf16 v[16:19], v[80:83], v[230:233], v[16:19]
	v_mfma_f32_16x16x32_bf16 v[48:51], v[88:91], v[230:233], v[48:51]
	ds_read_b128 v[124:127], v228 offset:38912
	s_waitcnt lgkmcnt(6)
	v_mfma_f32_16x16x32_bf16 v[20:23], v[80:83], v[234:237], v[20:23]
	v_mfma_f32_16x16x32_bf16 v[52:55], v[88:91], v[234:237], v[52:55]
	ds_read_b128 v[200:203], v228 offset:40960
	s_waitcnt lgkmcnt(6)
	v_mfma_f32_16x16x32_bf16 v[24:27], v[80:83], v[238:241], v[24:27]
	v_mfma_f32_16x16x32_bf16 v[56:59], v[88:91], v[238:241], v[56:59]
	ds_read_b128 v[204:207], v228 offset:43008
	s_waitcnt lgkmcnt(6)
	v_mfma_f32_16x16x32_bf16 v[28:31], v[80:83], v[242:245], v[28:31]
	v_mfma_f32_16x16x32_bf16 v[60:63], v[88:91], v[242:245], v[60:63]
	s_waitcnt vmcnt(8)
	s_barrier
	ds_read_b128 v[208:211], v228 offset:45056
	global_load_dwordx4 v[64:67], v142, s[84:85] offset:0
	s_waitcnt lgkmcnt(6)
	v_mfma_f32_16x16x32_bf16 v[0:3], v[84:87], v[112:115], v[0:3]
	v_mfma_f32_16x16x32_bf16 v[32:35], v[92:95], v[112:115], v[32:35]
	ds_read_b128 v[212:215], v228 offset:47104
	global_load_dwordx4 v[68:71], v142, s[84:85] offset:1024
	s_waitcnt lgkmcnt(6)
	v_mfma_f32_16x16x32_bf16 v[4:7], v[84:87], v[116:119], v[4:7]
	v_mfma_f32_16x16x32_bf16 v[36:39], v[92:95], v[116:119], v[36:39]
	ds_read_b128 v[230:233], v226 offset:49152
	global_load_dwordx4 v[72:75], v216, s[84:85] offset:0
	s_waitcnt lgkmcnt(6)
	v_mfma_f32_16x16x32_bf16 v[8:11], v[84:87], v[120:123], v[8:11]
	v_mfma_f32_16x16x32_bf16 v[40:43], v[92:95], v[120:123], v[40:43]
	ds_read_b128 v[234:237], v226 offset:51200
	global_load_dwordx4 v[76:79], v216, s[84:85] offset:1024
	s_add_u32 s84, s84, 0x800
	s_addc_u32 s85, s85, 0
	s_waitcnt lgkmcnt(6)
	v_mfma_f32_16x16x32_bf16 v[12:15], v[84:87], v[124:127], v[12:15]
	v_mfma_f32_16x16x32_bf16 v[44:47], v[92:95], v[124:127], v[44:47]
	ds_read_b128 v[238:241], v226 offset:53248
	s_add_u32 m0, s1, 16384
	s_nop 0
	global_load_lds_dwordx4 v218, s[86:87]
	s_waitcnt lgkmcnt(6)
	v_mfma_f32_16x16x32_bf16 v[16:19], v[84:87], v[200:203], v[16:19]
	v_mfma_f32_16x16x32_bf16 v[48:51], v[92:95], v[200:203], v[48:51]
	ds_read_b128 v[242:245], v226 offset:55296
	s_add_u32 m0, s1, 20480
	s_nop 0
	global_load_lds_dwordx4 v220, s[86:87]
	s_waitcnt lgkmcnt(6)
	v_mfma_f32_16x16x32_bf16 v[20:23], v[84:87], v[204:207], v[20:23]
	v_mfma_f32_16x16x32_bf16 v[52:55], v[92:95], v[204:207], v[52:55]
	ds_read_b128 v[112:115], v226 offset:57344
	s_add_u32 m0, s1, 24576
	s_nop 0
	global_load_lds_dwordx4 v222, s[86:87]
	s_waitcnt lgkmcnt(6)
	v_mfma_f32_16x16x32_bf16 v[24:27], v[84:87], v[208:211], v[24:27]
	v_mfma_f32_16x16x32_bf16 v[56:59], v[92:95], v[208:211], v[56:59]
	ds_read_b128 v[116:119], v226 offset:59392
	s_add_u32 m0, s1, 28672
	s_nop 0
	global_load_lds_dwordx4 v224, s[86:87]
	s_add_u32 s86, s86, 128
	s_addc_u32 s87, s87, 0
	s_waitcnt lgkmcnt(6)
	v_mfma_f32_16x16x32_bf16 v[28:31], v[84:87], v[212:215], v[28:31]
	v_mfma_f32_16x16x32_bf16 v[60:63], v[92:95], v[212:215], v[60:63]
	s_waitcnt vmcnt(12)
	ds_read_b128 v[120:123], v226 offset:61440
	s_waitcnt lgkmcnt(6)
	v_mfma_f32_16x16x32_bf16 v[0:3], v[96:99], v[230:233], v[0:3]
	v_mfma_f32_16x16x32_bf16 v[32:35], v[104:107], v[230:233], v[32:35]
	ds_read_b128 v[124:127], v226 offset:63488
	s_waitcnt lgkmcnt(6)
	v_mfma_f32_16x16x32_bf16 v[4:7], v[96:99], v[234:237], v[4:7]
	v_mfma_f32_16x16x32_bf16 v[36:39], v[104:107], v[234:237], v[36:39]
	ds_read_b128 v[200:203], v228 offset:49152
	s_waitcnt lgkmcnt(6)
	v_mfma_f32_16x16x32_bf16 v[8:11], v[96:99], v[238:241], v[8:11]
	v_mfma_f32_16x16x32_bf16 v[40:43], v[104:107], v[238:241], v[40:43]
	ds_read_b128 v[204:207], v228 offset:51200
	s_waitcnt lgkmcnt(6)
	v_mfma_f32_16x16x32_bf16 v[12:15], v[96:99], v[242:245], v[12:15]
	v_mfma_f32_16x16x32_bf16 v[44:47], v[104:107], v[242:245], v[44:47]
	ds_read_b128 v[208:211], v228 offset:53248
	s_waitcnt lgkmcnt(6)
	v_mfma_f32_16x16x32_bf16 v[16:19], v[96:99], v[112:115], v[16:19]
	v_mfma_f32_16x16x32_bf16 v[48:51], v[104:107], v[112:115], v[48:51]
	ds_read_b128 v[212:215], v228 offset:55296
	s_waitcnt lgkmcnt(6)
	v_mfma_f32_16x16x32_bf16 v[20:23], v[96:99], v[116:119], v[20:23]
	v_mfma_f32_16x16x32_bf16 v[52:55], v[104:107], v[116:119], v[52:55]
	ds_read_b128 v[230:233], v228 offset:57344
	s_waitcnt lgkmcnt(6)
	v_mfma_f32_16x16x32_bf16 v[24:27], v[96:99], v[120:123], v[24:27]
	v_mfma_f32_16x16x32_bf16 v[56:59], v[104:107], v[120:123], v[56:59]
	ds_read_b128 v[234:237], v228 offset:59392
	s_waitcnt lgkmcnt(6)
	v_mfma_f32_16x16x32_bf16 v[28:31], v[96:99], v[124:127], v[28:31]
	v_mfma_f32_16x16x32_bf16 v[60:63], v[104:107], v[124:127], v[60:63]
	s_waitcnt vmcnt(8)
	s_barrier
	ds_read_b128 v[238:241], v228 offset:61440
	global_load_dwordx4 v[80:83], v142, s[84:85] offset:0
	s_waitcnt lgkmcnt(6)
	v_mfma_f32_16x16x32_bf16 v[0:3], v[100:103], v[200:203], v[0:3]
	v_mfma_f32_16x16x32_bf16 v[32:35], v[108:111], v[200:203], v[32:35]
	ds_read_b128 v[242:245], v228 offset:63488
	global_load_dwordx4 v[84:87], v142, s[84:85] offset:1024
	s_waitcnt lgkmcnt(6)
	v_mfma_f32_16x16x32_bf16 v[4:7], v[100:103], v[204:207], v[4:7]
	v_mfma_f32_16x16x32_bf16 v[36:39], v[108:111], v[204:207], v[36:39]
	ds_read_b128 v[112:115], v226 offset:0
	global_load_dwordx4 v[88:91], v216, s[84:85] offset:0
	s_waitcnt lgkmcnt(6)
	v_mfma_f32_16x16x32_bf16 v[8:11], v[100:103], v[208:211], v[8:11]
	v_mfma_f32_16x16x32_bf16 v[40:43], v[108:111], v[208:211], v[40:43]
	ds_read_b128 v[116:119], v226 offset:2048
	global_load_dwordx4 v[92:95], v216, s[84:85] offset:1024
	s_add_u32 s84, s84, 0x800
	s_addc_u32 s85, s85, 0
	s_waitcnt lgkmcnt(6)
	v_mfma_f32_16x16x32_bf16 v[12:15], v[100:103], v[212:215], v[12:15]
	v_mfma_f32_16x16x32_bf16 v[44:47], v[108:111], v[212:215], v[44:47]
	ds_read_b128 v[120:123], v226 offset:4096
	s_add_u32 m0, s1, 32768
	s_nop 0
	global_load_lds_dwordx4 v218, s[86:87]
	s_waitcnt lgkmcnt(6)
	v_mfma_f32_16x16x32_bf16 v[16:19], v[100:103], v[230:233], v[16:19]
	v_mfma_f32_16x16x32_bf16 v[48:51], v[108:111], v[230:233], v[48:51]
	ds_read_b128 v[124:127], v226 offset:6144
	s_add_u32 m0, s1, 36864
	s_nop 0
	global_load_lds_dwordx4 v220, s[86:87]
	s_waitcnt lgkmcnt(6)
	v_mfma_f32_16x16x32_bf16 v[20:23], v[100:103], v[234:237], v[20:23]
	v_mfma_f32_16x16x32_bf16 v[52:55], v[108:111], v[234:237], v[52:55]
	ds_read_b128 v[200:203], v226 offset:8192
	s_add_u32 m0, s1, 40960
	s_nop 0
	global_load_lds_dwordx4 v222, s[86:87]
	s_waitcnt lgkmcnt(6)
	v_mfma_f32_16x16x32_bf16 v[24:27], v[100:103], v[238:241], v[24:27]
	v_mfma_f32_16x16x32_bf16 v[56:59], v[108:111], v[238:241], v[56:59]
	ds_read_b128 v[204:207], v226 offset:10240
	s_add_u32 m0, s1, 45056
	s_nop 0
	global_load_lds_dwordx4 v224, s[86:87]
	s_add_u32 s86, s86, 128
	s_addc_u32 s87, s87, 0
	s_waitcnt lgkmcnt(6)
	v_mfma_f32_16x16x32_bf16 v[28:31], v[100:103], v[242:245], v[28:31]
	v_mfma_f32_16x16x32_bf16 v[60:63], v[108:111], v[242:245], v[60:63]
	s_waitcnt vmcnt(12)
	ds_read_b128 v[208:211], v226 offset:12288
	s_waitcnt lgkmcnt(6)
	v_mfma_f32_16x16x32_bf16 v[0:3], v[64:67], v[112:115], v[0:3]
	v_mfma_f32_16x16x32_bf16 v[32:35], v[72:75], v[112:115], v[32:35]
	ds_read_b128 v[212:215], v226 offset:14336
	s_waitcnt lgkmcnt(6)
	v_mfma_f32_16x16x32_bf16 v[4:7], v[64:67], v[116:119], v[4:7]
	v_mfma_f32_16x16x32_bf16 v[36:39], v[72:75], v[116:119], v[36:39]
	ds_read_b128 v[230:233], v228 offset:0
	s_waitcnt lgkmcnt(6)
	v_mfma_f32_16x16x32_bf16 v[8:11], v[64:67], v[120:123], v[8:11]
	v_mfma_f32_16x16x32_bf16 v[40:43], v[72:75], v[120:123], v[40:43]
	ds_read_b128 v[234:237], v228 offset:2048
	s_waitcnt lgkmcnt(6)
	v_mfma_f32_16x16x32_bf16 v[12:15], v[64:67], v[124:127], v[12:15]
	v_mfma_f32_16x16x32_bf16 v[44:47], v[72:75], v[124:127], v[44:47]
	ds_read_b128 v[238:241], v228 offset:4096
	s_waitcnt lgkmcnt(6)
	v_mfma_f32_16x16x32_bf16 v[16:19], v[64:67], v[200:203], v[16:19]
	v_mfma_f32_16x16x32_bf16 v[48:51], v[72:75], v[200:203], v[48:51]
	ds_read_b128 v[242:245], v228 offset:6144
	s_waitcnt lgkmcnt(6)
	v_mfma_f32_16x16x32_bf16 v[20:23], v[64:67], v[204:207], v[20:23]
	v_mfma_f32_16x16x32_bf16 v[52:55], v[72:75], v[204:207], v[52:55]
	ds_read_b128 v[112:115], v228 offset:8192
	s_waitcnt lgkmcnt(6)
	v_mfma_f32_16x16x32_bf16 v[24:27], v[64:67], v[208:211], v[24:27]
	v_mfma_f32_16x16x32_bf16 v[56:59], v[72:75], v[208:211], v[56:59]
	ds_read_b128 v[116:119], v228 offset:10240
	s_waitcnt lgkmcnt(6)
	v_mfma_f32_16x16x32_bf16 v[28:31], v[64:67], v[212:215], v[28:31]
	v_mfma_f32_16x16x32_bf16 v[60:63], v[72:75], v[212:215], v[60:63]
	s_waitcnt vmcnt(8)
	s_barrier
	ds_read_b128 v[120:123], v228 offset:12288
	global_load_dwordx4 v[96:99], v142, s[84:85] offset:0
	s_waitcnt lgkmcnt(6)
	v_mfma_f32_16x16x32_bf16 v[0:3], v[68:71], v[230:233], v[0:3]
	v_mfma_f32_16x16x32_bf16 v[32:35], v[76:79], v[230:233], v[32:35]
	ds_read_b128 v[124:127], v228 offset:14336
	global_load_dwordx4 v[100:103], v142, s[84:85] offset:1024
	s_waitcnt lgkmcnt(6)
	v_mfma_f32_16x16x32_bf16 v[4:7], v[68:71], v[234:237], v[4:7]
	v_mfma_f32_16x16x32_bf16 v[36:39], v[76:79], v[234:237], v[36:39]
	ds_read_b128 v[200:203], v226 offset:16384
	global_load_dwordx4 v[104:107], v216, s[84:85] offset:0
	s_waitcnt lgkmcnt(6)
	v_mfma_f32_16x16x32_bf16 v[8:11], v[68:71], v[238:241], v[8:11]
	v_mfma_f32_16x16x32_bf16 v[40:43], v[76:79], v[238:241], v[40:43]
	ds_read_b128 v[204:207], v226 offset:18432
	global_load_dwordx4 v[108:111], v216, s[84:85] offset:1024
	s_add_u32 s84, s84, 0x800
	s_addc_u32 s85, s85, 0
	s_waitcnt lgkmcnt(6)
	v_mfma_f32_16x16x32_bf16 v[12:15], v[68:71], v[242:245], v[12:15]
	v_mfma_f32_16x16x32_bf16 v[44:47], v[76:79], v[242:245], v[44:47]
	ds_read_b128 v[208:211], v226 offset:20480
	s_add_u32 m0, s1, 49152
	s_nop 0
	global_load_lds_dwordx4 v218, s[86:87]
	s_waitcnt lgkmcnt(6)
	v_mfma_f32_16x16x32_bf16 v[16:19], v[68:71], v[112:115], v[16:19]
	v_mfma_f32_16x16x32_bf16 v[48:51], v[76:79], v[112:115], v[48:51]
	ds_read_b128 v[212:215], v226 offset:22528
	s_add_u32 m0, s1, 53248
	s_nop 0
	global_load_lds_dwordx4 v220, s[86:87]
	s_waitcnt lgkmcnt(6)
	v_mfma_f32_16x16x32_bf16 v[20:23], v[68:71], v[116:119], v[20:23]
	v_mfma_f32_16x16x32_bf16 v[52:55], v[76:79], v[116:119], v[52:55]
	ds_read_b128 v[230:233], v226 offset:24576
	s_add_u32 m0, s1, 57344
	s_nop 0
	global_load_lds_dwordx4 v222, s[86:87]
	s_waitcnt lgkmcnt(6)
	v_mfma_f32_16x16x32_bf16 v[24:27], v[68:71], v[120:123], v[24:27]
	v_mfma_f32_16x16x32_bf16 v[56:59], v[76:79], v[120:123], v[56:59]
	ds_read_b128 v[234:237], v226 offset:26624
	s_add_u32 m0, s1, 61440
	s_nop 0
	global_load_lds_dwordx4 v224, s[86:87]
	s_add_u32 s86, s86, 128
	s_addc_u32 s87, s87, 0
	s_waitcnt lgkmcnt(6)
	v_mfma_f32_16x16x32_bf16 v[28:31], v[68:71], v[124:127], v[28:31]
	v_mfma_f32_16x16x32_bf16 v[60:63], v[76:79], v[124:127], v[60:63]
	s_waitcnt vmcnt(12)
	ds_read_b128 v[238:241], v226 offset:28672
	s_waitcnt lgkmcnt(6)
	v_mfma_f32_16x16x32_bf16 v[0:3], v[80:83], v[200:203], v[0:3]
	v_mfma_f32_16x16x32_bf16 v[32:35], v[88:91], v[200:203], v[32:35]
	ds_read_b128 v[242:245], v226 offset:30720
	s_waitcnt lgkmcnt(6)
	v_mfma_f32_16x16x32_bf16 v[4:7], v[80:83], v[204:207], v[4:7]
	v_mfma_f32_16x16x32_bf16 v[36:39], v[88:91], v[204:207], v[36:39]
	ds_read_b128 v[112:115], v228 offset:16384
	s_waitcnt lgkmcnt(6)
	v_mfma_f32_16x16x32_bf16 v[8:11], v[80:83], v[208:211], v[8:11]
	v_mfma_f32_16x16x32_bf16 v[40:43], v[88:91], v[208:211], v[40:43]
	ds_read_b128 v[116:119], v228 offset:18432
	s_waitcnt lgkmcnt(6)
	v_mfma_f32_16x16x32_bf16 v[12:15], v[80:83], v[212:215], v[12:15]
	v_mfma_f32_16x16x32_bf16 v[44:47], v[88:91], v[212:215], v[44:47]
	ds_read_b128 v[120:123], v228 offset:20480
	s_waitcnt lgkmcnt(6)
	v_mfma_f32_16x16x32_bf16 v[16:19], v[80:83], v[230:233], v[16:19]
	v_mfma_f32_16x16x32_bf16 v[48:51], v[88:91], v[230:233], v[48:51]
	ds_read_b128 v[124:127], v228 offset:22528
	s_waitcnt lgkmcnt(6)
	v_mfma_f32_16x16x32_bf16 v[20:23], v[80:83], v[234:237], v[20:23]
	v_mfma_f32_16x16x32_bf16 v[52:55], v[88:91], v[234:237], v[52:55]
	ds_read_b128 v[200:203], v228 offset:24576
	s_waitcnt lgkmcnt(6)
	v_mfma_f32_16x16x32_bf16 v[24:27], v[80:83], v[238:241], v[24:27]
	v_mfma_f32_16x16x32_bf16 v[56:59], v[88:91], v[238:241], v[56:59]
	ds_read_b128 v[204:207], v228 offset:26624
	s_waitcnt lgkmcnt(6)
	v_mfma_f32_16x16x32_bf16 v[28:31], v[80:83], v[242:245], v[28:31]
	v_mfma_f32_16x16x32_bf16 v[60:63], v[88:91], v[242:245], v[60:63]
	s_waitcnt vmcnt(8)
	s_barrier
	ds_read_b128 v[208:211], v228 offset:28672
	global_load_dwordx4 v[64:67], v142, s[84:85] offset:0
	s_waitcnt lgkmcnt(6)
	v_mfma_f32_16x16x32_bf16 v[0:3], v[84:87], v[112:115], v[0:3]
	v_mfma_f32_16x16x32_bf16 v[32:35], v[92:95], v[112:115], v[32:35]
	ds_read_b128 v[212:215], v228 offset:30720
	global_load_dwordx4 v[68:71], v142, s[84:85] offset:1024
	s_waitcnt lgkmcnt(6)
	v_mfma_f32_16x16x32_bf16 v[4:7], v[84:87], v[116:119], v[4:7]
	v_mfma_f32_16x16x32_bf16 v[36:39], v[92:95], v[116:119], v[36:39]
	ds_read_b128 v[230:233], v226 offset:32768
	global_load_dwordx4 v[72:75], v216, s[84:85] offset:0
	s_waitcnt lgkmcnt(6)
	v_mfma_f32_16x16x32_bf16 v[8:11], v[84:87], v[120:123], v[8:11]
	v_mfma_f32_16x16x32_bf16 v[40:43], v[92:95], v[120:123], v[40:43]
	ds_read_b128 v[234:237], v226 offset:34816
	global_load_dwordx4 v[76:79], v216, s[84:85] offset:1024
	s_add_u32 s84, s84, 0x800
	s_addc_u32 s85, s85, 0
	s_waitcnt lgkmcnt(6)
	v_mfma_f32_16x16x32_bf16 v[12:15], v[84:87], v[124:127], v[12:15]
	v_mfma_f32_16x16x32_bf16 v[44:47], v[92:95], v[124:127], v[44:47]
	ds_read_b128 v[238:241], v226 offset:36864
	s_waitcnt lgkmcnt(6)
	v_mfma_f32_16x16x32_bf16 v[16:19], v[84:87], v[200:203], v[16:19]
	v_mfma_f32_16x16x32_bf16 v[48:51], v[92:95], v[200:203], v[48:51]
	ds_read_b128 v[242:245], v226 offset:38912
	s_waitcnt lgkmcnt(6)
	v_mfma_f32_16x16x32_bf16 v[20:23], v[84:87], v[204:207], v[20:23]
	v_mfma_f32_16x16x32_bf16 v[52:55], v[92:95], v[204:207], v[52:55]
	ds_read_b128 v[112:115], v226 offset:40960
	s_waitcnt lgkmcnt(6)
	v_mfma_f32_16x16x32_bf16 v[24:27], v[84:87], v[208:211], v[24:27]
	v_mfma_f32_16x16x32_bf16 v[56:59], v[92:95], v[208:211], v[56:59]
	ds_read_b128 v[116:119], v226 offset:43008
	s_waitcnt lgkmcnt(6)
	v_mfma_f32_16x16x32_bf16 v[28:31], v[84:87], v[212:215], v[28:31]
	v_mfma_f32_16x16x32_bf16 v[60:63], v[92:95], v[212:215], v[60:63]
	s_waitcnt vmcnt(8)
	ds_read_b128 v[120:123], v226 offset:45056
	s_waitcnt lgkmcnt(6)
	v_mfma_f32_16x16x32_bf16 v[0:3], v[96:99], v[230:233], v[0:3]
	v_mfma_f32_16x16x32_bf16 v[32:35], v[104:107], v[230:233], v[32:35]
	ds_read_b128 v[124:127], v226 offset:47104
	s_waitcnt lgkmcnt(6)
	v_mfma_f32_16x16x32_bf16 v[4:7], v[96:99], v[234:237], v[4:7]
	v_mfma_f32_16x16x32_bf16 v[36:39], v[104:107], v[234:237], v[36:39]
	ds_read_b128 v[200:203], v228 offset:32768
	s_waitcnt lgkmcnt(6)
	v_mfma_f32_16x16x32_bf16 v[8:11], v[96:99], v[238:241], v[8:11]
	v_mfma_f32_16x16x32_bf16 v[40:43], v[104:107], v[238:241], v[40:43]
	ds_read_b128 v[204:207], v228 offset:34816
	s_waitcnt lgkmcnt(6)
	v_mfma_f32_16x16x32_bf16 v[12:15], v[96:99], v[242:245], v[12:15]
	v_mfma_f32_16x16x32_bf16 v[44:47], v[104:107], v[242:245], v[44:47]
	ds_read_b128 v[208:211], v228 offset:36864
	s_waitcnt lgkmcnt(6)
	v_mfma_f32_16x16x32_bf16 v[16:19], v[96:99], v[112:115], v[16:19]
	v_mfma_f32_16x16x32_bf16 v[48:51], v[104:107], v[112:115], v[48:51]
	ds_read_b128 v[212:215], v228 offset:38912
	s_waitcnt lgkmcnt(6)
	v_mfma_f32_16x16x32_bf16 v[20:23], v[96:99], v[116:119], v[20:23]
	v_mfma_f32_16x16x32_bf16 v[52:55], v[104:107], v[116:119], v[52:55]
	ds_read_b128 v[230:233], v228 offset:40960
	s_waitcnt lgkmcnt(6)
	v_mfma_f32_16x16x32_bf16 v[24:27], v[96:99], v[120:123], v[24:27]
	v_mfma_f32_16x16x32_bf16 v[56:59], v[104:107], v[120:123], v[56:59]
	ds_read_b128 v[234:237], v228 offset:43008
	s_waitcnt lgkmcnt(6)
	v_mfma_f32_16x16x32_bf16 v[28:31], v[96:99], v[124:127], v[28:31]
	v_mfma_f32_16x16x32_bf16 v[60:63], v[104:107], v[124:127], v[60:63]
	s_waitcnt vmcnt(4)
	s_barrier
	ds_read_b128 v[238:241], v228 offset:45056
	s_waitcnt lgkmcnt(6)
	v_mfma_f32_16x16x32_bf16 v[0:3], v[100:103], v[200:203], v[0:3]
	v_mfma_f32_16x16x32_bf16 v[32:35], v[108:111], v[200:203], v[32:35]
	ds_read_b128 v[242:245], v228 offset:47104
	s_waitcnt lgkmcnt(6)
	v_mfma_f32_16x16x32_bf16 v[4:7], v[100:103], v[204:207], v[4:7]
	v_mfma_f32_16x16x32_bf16 v[36:39], v[108:111], v[204:207], v[36:39]
	ds_read_b128 v[112:115], v226 offset:49152
	s_waitcnt lgkmcnt(6)
	v_mfma_f32_16x16x32_bf16 v[8:11], v[100:103], v[208:211], v[8:11]
	v_mfma_f32_16x16x32_bf16 v[40:43], v[108:111], v[208:211], v[40:43]
	ds_read_b128 v[116:119], v226 offset:51200
	s_waitcnt lgkmcnt(6)
	v_mfma_f32_16x16x32_bf16 v[12:15], v[100:103], v[212:215], v[12:15]
	v_mfma_f32_16x16x32_bf16 v[44:47], v[108:111], v[212:215], v[44:47]
	ds_read_b128 v[120:123], v226 offset:53248
	s_waitcnt lgkmcnt(6)
	v_mfma_f32_16x16x32_bf16 v[16:19], v[100:103], v[230:233], v[16:19]
	v_mfma_f32_16x16x32_bf16 v[48:51], v[108:111], v[230:233], v[48:51]
	ds_read_b128 v[124:127], v226 offset:55296
	s_waitcnt lgkmcnt(6)
	v_mfma_f32_16x16x32_bf16 v[20:23], v[100:103], v[234:237], v[20:23]
	v_mfma_f32_16x16x32_bf16 v[52:55], v[108:111], v[234:237], v[52:55]
	ds_read_b128 v[200:203], v226 offset:57344
	s_waitcnt lgkmcnt(6)
	v_mfma_f32_16x16x32_bf16 v[24:27], v[100:103], v[238:241], v[24:27]
	v_mfma_f32_16x16x32_bf16 v[56:59], v[108:111], v[238:241], v[56:59]
	ds_read_b128 v[204:207], v226 offset:59392
	s_waitcnt lgkmcnt(6)
	v_mfma_f32_16x16x32_bf16 v[28:31], v[100:103], v[242:245], v[28:31]
	v_mfma_f32_16x16x32_bf16 v[60:63], v[108:111], v[242:245], v[60:63]
	s_waitcnt vmcnt(0)
	ds_read_b128 v[208:211], v226 offset:61440
	s_waitcnt lgkmcnt(6)
	v_mfma_f32_16x16x32_bf16 v[0:3], v[64:67], v[112:115], v[0:3]
	v_mfma_f32_16x16x32_bf16 v[32:35], v[72:75], v[112:115], v[32:35]
	ds_read_b128 v[212:215], v226 offset:63488
	s_waitcnt lgkmcnt(6)
	v_mfma_f32_16x16x32_bf16 v[4:7], v[64:67], v[116:119], v[4:7]
	v_mfma_f32_16x16x32_bf16 v[36:39], v[72:75], v[116:119], v[36:39]
	ds_read_b128 v[230:233], v228 offset:49152
	s_waitcnt lgkmcnt(6)
	v_mfma_f32_16x16x32_bf16 v[8:11], v[64:67], v[120:123], v[8:11]
	v_mfma_f32_16x16x32_bf16 v[40:43], v[72:75], v[120:123], v[40:43]
	ds_read_b128 v[234:237], v228 offset:51200
	s_waitcnt lgkmcnt(6)
	v_mfma_f32_16x16x32_bf16 v[12:15], v[64:67], v[124:127], v[12:15]
	v_mfma_f32_16x16x32_bf16 v[44:47], v[72:75], v[124:127], v[44:47]
	ds_read_b128 v[238:241], v228 offset:53248
	s_waitcnt lgkmcnt(6)
	v_mfma_f32_16x16x32_bf16 v[16:19], v[64:67], v[200:203], v[16:19]
	v_mfma_f32_16x16x32_bf16 v[48:51], v[72:75], v[200:203], v[48:51]
	ds_read_b128 v[242:245], v228 offset:55296
	s_waitcnt lgkmcnt(6)
	v_mfma_f32_16x16x32_bf16 v[20:23], v[64:67], v[204:207], v[20:23]
	v_mfma_f32_16x16x32_bf16 v[52:55], v[72:75], v[204:207], v[52:55]
	ds_read_b128 v[112:115], v228 offset:57344
	s_waitcnt lgkmcnt(6)
	v_mfma_f32_16x16x32_bf16 v[24:27], v[64:67], v[208:211], v[24:27]
	v_mfma_f32_16x16x32_bf16 v[56:59], v[72:75], v[208:211], v[56:59]
	ds_read_b128 v[116:119], v228 offset:59392
	s_waitcnt lgkmcnt(6)
	v_mfma_f32_16x16x32_bf16 v[28:31], v[64:67], v[212:215], v[28:31]
	v_mfma_f32_16x16x32_bf16 v[60:63], v[72:75], v[212:215], v[60:63]
	ds_read_b128 v[120:123], v228 offset:61440
	s_waitcnt lgkmcnt(6)
	v_mfma_f32_16x16x32_bf16 v[0:3], v[68:71], v[230:233], v[0:3]
	v_mfma_f32_16x16x32_bf16 v[32:35], v[76:79], v[230:233], v[32:35]
	ds_read_b128 v[124:127], v228 offset:63488
	s_waitcnt lgkmcnt(6)
	v_mfma_f32_16x16x32_bf16 v[4:7], v[68:71], v[234:237], v[4:7]
	v_mfma_f32_16x16x32_bf16 v[36:39], v[76:79], v[234:237], v[36:39]
	s_waitcnt lgkmcnt(5)
	v_mfma_f32_16x16x32_bf16 v[8:11], v[68:71], v[238:241], v[8:11]
	v_mfma_f32_16x16x32_bf16 v[40:43], v[76:79], v[238:241], v[40:43]
	s_waitcnt lgkmcnt(4)
	v_mfma_f32_16x16x32_bf16 v[12:15], v[68:71], v[242:245], v[12:15]
	v_mfma_f32_16x16x32_bf16 v[44:47], v[76:79], v[242:245], v[44:47]
	s_waitcnt lgkmcnt(3)
	v_mfma_f32_16x16x32_bf16 v[16:19], v[68:71], v[112:115], v[16:19]
	v_mfma_f32_16x16x32_bf16 v[48:51], v[76:79], v[112:115], v[48:51]
	s_waitcnt lgkmcnt(2)
	v_mfma_f32_16x16x32_bf16 v[20:23], v[68:71], v[116:119], v[20:23]
	v_mfma_f32_16x16x32_bf16 v[52:55], v[76:79], v[116:119], v[52:55]
	s_waitcnt lgkmcnt(1)
	v_mfma_f32_16x16x32_bf16 v[24:27], v[68:71], v[120:123], v[24:27]
	v_mfma_f32_16x16x32_bf16 v[56:59], v[76:79], v[120:123], v[56:59]
	s_waitcnt lgkmcnt(0)
	v_mfma_f32_16x16x32_bf16 v[28:31], v[68:71], v[124:127], v[28:31]
	v_mfma_f32_16x16x32_bf16 v[60:63], v[76:79], v[124:127], v[60:63]
	s_nop 7
	s_nop 7
	s_waitcnt vmcnt(0) lgkmcnt(0)
	s_barrier
	s_mov_b64 s[6:7], -1
	s_cmp_lt_i32 s77, 5
	s_cbranch_scc1 .LBB0_175
	v_mul_f32_e32 v64, 0xbfb8aa3b, v2
	v_mul_f32_e32 v65, 0xbfb8aa3b, v3
	v_exp_f32_e32 v64, v64
	v_exp_f32_e32 v65, v65
	v_mul_f32_e32 v66, 0xbfb8aa3b, v0
	v_mul_f32_e32 v67, 0xbfb8aa3b, v1
	v_exp_f32_e32 v66, v66
	v_pk_add_f32 v[64:65], v[64:65], 1.0 op_sel_hi:[1,0]
	v_exp_f32_e32 v67, v67
	v_div_scale_f32 v70, s[4:5], v65, v65, v3
	v_rcp_f32_e32 v71, v70
	v_pk_add_f32 v[68:69], v[66:67], 1.0 op_sel_hi:[1,0]
	v_mul_f32_e32 v73, 0xbfb8aa3b, v5
	v_exp_f32_e32 v73, v73
	v_fma_f32 v66, -v70, v71, 1.0
	v_fmac_f32_e32 v71, v66, v71
	v_div_scale_f32 v66, vcc, v3, v65, v3
	v_mul_f32_e32 v67, v66, v71
	v_fma_f32 v72, -v70, v67, v66
	v_fmac_f32_e32 v67, v72, v71
	v_fma_f32 v66, -v70, v67, v66
	v_div_scale_f32 v70, s[4:5], v64, v64, v2
	v_rcp_f32_e32 v72, v70
	v_div_fmas_f32 v66, v66, v71, v67
	v_div_fixup_f32 v67, v66, v65, v3
	v_mul_f32_e32 v81, 0xbfb8aa3b, v13
	v_fma_f32 v65, -v70, v72, 1.0
	v_fmac_f32_e32 v72, v65, v72
	v_div_scale_f32 v65, vcc, v2, v64, v2
	v_mul_f32_e32 v66, v65, v72
	v_fma_f32 v71, -v70, v66, v65
	v_fmac_f32_e32 v66, v71, v72
	v_fma_f32 v65, -v70, v66, v65
	v_div_scale_f32 v70, s[4:5], v69, v69, v1
	v_rcp_f32_e32 v71, v70
	v_div_fmas_f32 v65, v65, v72, v66
	v_div_fixup_f32 v66, v65, v64, v2
	v_exp_f32_e32 v81, v81
	v_fma_f32 v64, -v70, v71, 1.0
	v_fmac_f32_e32 v71, v64, v71
	v_div_scale_f32 v64, vcc, v1, v69, v1
	v_mul_f32_e32 v65, v64, v71
	v_fma_f32 v72, -v70, v65, v64
	v_fmac_f32_e32 v65, v72, v71
	v_fma_f32 v64, -v70, v65, v64
	v_div_scale_f32 v70, s[4:5], v68, v68, v0
	v_rcp_f32_e32 v74, v70
	v_div_fmas_f32 v64, v64, v71, v65
	v_div_fixup_f32 v65, v64, v69, v1
	v_mul_f32_e32 v72, 0xbfb8aa3b, v4
	v_fma_f32 v64, -v70, v74, 1.0
	v_fmac_f32_e32 v74, v64, v74
	v_div_scale_f32 v64, vcc, v0, v68, v0
	v_mul_f32_e32 v69, v64, v74
	v_fma_f32 v71, -v70, v69, v64
	v_fmac_f32_e32 v69, v71, v74
	v_fma_f32 v64, -v70, v69, v64
	v_mul_f32_e32 v70, 0xbfb8aa3b, v6
	v_mul_f32_e32 v71, 0xbfb8aa3b, v7
	v_exp_f32_e32 v70, v70
	v_exp_f32_e32 v71, v71
	v_exp_f32_e32 v72, v72
	v_div_fmas_f32 v64, v64, v74, v69
	v_div_fixup_f32 v64, v64, v68, v0
	v_pk_add_f32 v[70:71], v[70:71], 1.0 op_sel_hi:[1,0]
	v_pk_add_f32 v[68:69], v[72:73], 1.0 op_sel_hi:[1,0]
	v_div_scale_f32 v75, s[4:5], v71, v71, v7
	v_rcp_f32_e32 v76, v75
	v_mul_f32_e32 v89, 0xbfb8aa3b, v21
	v_exp_f32_e32 v89, v89
	v_mul_f32_e32 v97, 0xbfb8aa3b, v29
	v_fma_f32 v72, -v75, v76, 1.0
	v_fmac_f32_e32 v76, v72, v76
	v_div_scale_f32 v72, vcc, v7, v71, v7
	v_mul_f32_e32 v73, v72, v76
	v_fma_f32 v74, -v75, v73, v72
	v_fmac_f32_e32 v73, v74, v76
	v_div_scale_f32 v74, s[4:5], v70, v70, v6
	v_fma_f32 v72, -v75, v73, v72
	v_rcp_f32_e32 v75, v74
	v_div_fmas_f32 v72, v72, v76, v73
	v_div_fixup_f32 v71, v72, v71, v7
	v_exp_f32_e32 v97, v97
	v_fma_f32 v72, -v74, v75, 1.0
	v_fmac_f32_e32 v75, v72, v75
	v_div_scale_f32 v72, vcc, v6, v70, v6
	v_mul_f32_e32 v73, v72, v75
	v_fma_f32 v76, -v74, v73, v72
	v_fmac_f32_e32 v73, v76, v75
	v_fma_f32 v72, -v74, v73, v72
	v_div_scale_f32 v74, s[4:5], v69, v69, v5
	v_rcp_f32_e32 v76, v74
	v_div_fmas_f32 v72, v72, v75, v73
	v_div_fixup_f32 v70, v72, v70, v6
	v_mul_f32_e32 v105, 0xbfb8aa3b, v37
	v_fma_f32 v72, -v74, v76, 1.0
	v_fmac_f32_e32 v76, v72, v76
	v_div_scale_f32 v72, vcc, v5, v69, v5
	v_mul_f32_e32 v73, v72, v76
	v_fma_f32 v75, -v74, v73, v72
	v_fmac_f32_e32 v73, v75, v76
	v_fma_f32 v72, -v74, v73, v72
	v_div_scale_f32 v74, s[4:5], v68, v68, v4
	v_rcp_f32_e32 v77, v74
	v_div_fmas_f32 v72, v72, v76, v73
	v_div_fixup_f32 v69, v72, v69, v5
	v_mul_f32_e32 v75, 0xbfb8aa3b, v9
	v_fma_f32 v72, -v74, v77, 1.0
	v_fmac_f32_e32 v77, v72, v77
	v_div_scale_f32 v72, vcc, v4, v68, v4
	v_mul_f32_e32 v76, v72, v77
	v_fma_f32 v73, -v74, v76, v72
	v_fmac_f32_e32 v76, v73, v77
	v_fma_f32 v78, -v74, v76, v72
	v_mul_f32_e32 v72, 0xbfb8aa3b, v10
	v_mul_f32_e32 v73, 0xbfb8aa3b, v11
	v_exp_f32_e32 v72, v72
	v_exp_f32_e32 v73, v73
	v_mul_f32_e32 v74, 0xbfb8aa3b, v8
	v_exp_f32_e32 v74, v74
	v_exp_f32_e32 v75, v75
	v_pk_add_f32 v[72:73], v[72:73], 1.0 op_sel_hi:[1,0]
	v_div_fmas_f32 v76, v78, v77, v76
	v_div_scale_f32 v79, s[4:5], v73, v73, v11
	v_rcp_f32_e32 v80, v79
	v_div_fixup_f32 v68, v76, v68, v4
	v_pk_add_f32 v[76:77], v[74:75], 1.0 op_sel_hi:[1,0]
	v_exp_f32_e32 v105, v105
	v_fma_f32 v74, -v79, v80, 1.0
	v_fmac_f32_e32 v80, v74, v80
	v_div_scale_f32 v74, vcc, v11, v73, v11
	v_mul_f32_e32 v75, v74, v80
	v_fma_f32 v78, -v79, v75, v74
	v_fmac_f32_e32 v75, v78, v80
	v_div_scale_f32 v78, s[4:5], v72, v72, v10
	v_fma_f32 v74, -v79, v75, v74
	v_rcp_f32_e32 v79, v78
	v_div_fmas_f32 v74, v74, v80, v75
	v_div_fixup_f32 v75, v74, v73, v11
	v_mul_f32_e32 v113, 0xbfb8aa3b, v45
	v_fma_f32 v73, -v78, v79, 1.0
	v_fmac_f32_e32 v79, v73, v79
	v_div_scale_f32 v73, vcc, v10, v72, v10
	v_mul_f32_e32 v74, v73, v79
	v_fma_f32 v80, -v78, v74, v73
	v_fmac_f32_e32 v74, v80, v79
	v_fma_f32 v73, -v78, v74, v73
	v_div_scale_f32 v78, s[4:5], v77, v77, v9
	v_rcp_f32_e32 v80, v78
	v_div_fmas_f32 v73, v73, v79, v74
	v_div_fixup_f32 v74, v73, v72, v10
	v_exp_f32_e32 v113, v113
	v_fma_f32 v72, -v78, v80, 1.0
	v_fmac_f32_e32 v80, v72, v80
	v_div_scale_f32 v72, vcc, v9, v77, v9
	v_mul_f32_e32 v73, v72, v80
	v_fma_f32 v79, -v78, v73, v72
	v_fmac_f32_e32 v73, v79, v80
	v_fma_f32 v72, -v78, v73, v72
	v_div_scale_f32 v78, s[4:5], v76, v76, v8
	v_rcp_f32_e32 v82, v78
	v_div_fmas_f32 v72, v72, v80, v73
	v_div_fixup_f32 v73, v72, v77, v9
	v_mul_f32_e32 v80, 0xbfb8aa3b, v12
	v_fma_f32 v72, -v78, v82, 1.0
	v_fmac_f32_e32 v82, v72, v82
	v_div_scale_f32 v72, vcc, v8, v76, v8
	v_mul_f32_e32 v77, v72, v82
	v_fma_f32 v79, -v78, v77, v72
	v_fmac_f32_e32 v77, v79, v82
	v_fma_f32 v72, -v78, v77, v72
	v_mul_f32_e32 v78, 0xbfb8aa3b, v14
	v_mul_f32_e32 v79, 0xbfb8aa3b, v15
	v_exp_f32_e32 v78, v78
	v_exp_f32_e32 v79, v79
	v_exp_f32_e32 v80, v80
	v_div_fmas_f32 v72, v72, v82, v77
	v_div_fixup_f32 v72, v72, v76, v8
	v_pk_add_f32 v[78:79], v[78:79], 1.0 op_sel_hi:[1,0]
	v_pk_add_f32 v[76:77], v[80:81], 1.0 op_sel_hi:[1,0]
	v_div_scale_f32 v83, s[4:5], v79, v79, v15
	v_rcp_f32_e32 v84, v83
	v_mul_f32_e32 v121, 0xbfb8aa3b, v53
	v_exp_f32_e32 v121, v121
	s_mov_b64 s[6:7], 0
	v_fma_f32 v80, -v83, v84, 1.0
	v_fmac_f32_e32 v84, v80, v84
	v_div_scale_f32 v80, vcc, v15, v79, v15
	v_mul_f32_e32 v81, v80, v84
	v_fma_f32 v82, -v83, v81, v80
	v_fmac_f32_e32 v81, v82, v84
	v_div_scale_f32 v82, s[4:5], v78, v78, v14
	v_fma_f32 v80, -v83, v81, v80
	v_rcp_f32_e32 v83, v82
	v_div_fmas_f32 v80, v80, v84, v81
	v_div_fixup_f32 v79, v80, v79, v15
	v_fma_f32 v80, -v82, v83, 1.0
	v_fmac_f32_e32 v83, v80, v83
	v_div_scale_f32 v80, vcc, v14, v78, v14
	v_mul_f32_e32 v81, v80, v83
	v_fma_f32 v84, -v82, v81, v80
	v_fmac_f32_e32 v81, v84, v83
	v_fma_f32 v80, -v82, v81, v80
	v_div_scale_f32 v82, s[4:5], v77, v77, v13
	v_rcp_f32_e32 v84, v82
	v_div_fmas_f32 v80, v80, v83, v81
	v_div_fixup_f32 v78, v80, v78, v14
	v_fma_f32 v80, -v82, v84, 1.0
	v_fmac_f32_e32 v84, v80, v84
	v_div_scale_f32 v80, vcc, v13, v77, v13
	v_mul_f32_e32 v81, v80, v84
	v_fma_f32 v83, -v82, v81, v80
	v_fmac_f32_e32 v81, v83, v84
	v_fma_f32 v80, -v82, v81, v80
	v_div_scale_f32 v82, s[4:5], v76, v76, v12
	v_rcp_f32_e32 v85, v82
	v_div_fmas_f32 v80, v80, v84, v81
	v_div_fixup_f32 v77, v80, v77, v13
	v_mul_f32_e32 v83, 0xbfb8aa3b, v17
	v_fma_f32 v80, -v82, v85, 1.0
	v_fmac_f32_e32 v85, v80, v85
	v_div_scale_f32 v80, vcc, v12, v76, v12
	v_mul_f32_e32 v84, v80, v85
	v_fma_f32 v81, -v82, v84, v80
	v_fmac_f32_e32 v84, v81, v85
	v_fma_f32 v86, -v82, v84, v80
	v_mul_f32_e32 v80, 0xbfb8aa3b, v18
	v_mul_f32_e32 v81, 0xbfb8aa3b, v19
	v_exp_f32_e32 v80, v80
	v_exp_f32_e32 v81, v81
	v_mul_f32_e32 v82, 0xbfb8aa3b, v16
	v_exp_f32_e32 v82, v82
	v_exp_f32_e32 v83, v83
	v_pk_add_f32 v[80:81], v[80:81], 1.0 op_sel_hi:[1,0]
	v_div_fmas_f32 v84, v86, v85, v84
	v_div_scale_f32 v87, s[4:5], v81, v81, v19
	v_rcp_f32_e32 v88, v87
	v_div_fixup_f32 v76, v84, v76, v12
	v_pk_add_f32 v[84:85], v[82:83], 1.0 op_sel_hi:[1,0]
	v_fma_f32 v82, -v87, v88, 1.0
	v_fmac_f32_e32 v88, v82, v88
	v_div_scale_f32 v82, vcc, v19, v81, v19
	v_mul_f32_e32 v83, v82, v88
	v_fma_f32 v86, -v87, v83, v82
	v_fmac_f32_e32 v83, v86, v88
	v_div_scale_f32 v86, s[4:5], v80, v80, v18
	v_fma_f32 v82, -v87, v83, v82
	v_rcp_f32_e32 v87, v86
	v_div_fmas_f32 v82, v82, v88, v83
	v_div_fixup_f32 v83, v82, v81, v19
	v_fma_f32 v81, -v86, v87, 1.0
	v_fmac_f32_e32 v87, v81, v87
	v_div_scale_f32 v81, vcc, v18, v80, v18
	v_mul_f32_e32 v82, v81, v87
	v_fma_f32 v88, -v86, v82, v81
	v_fmac_f32_e32 v82, v88, v87
	v_fma_f32 v81, -v86, v82, v81
	v_div_scale_f32 v86, s[4:5], v85, v85, v17
	v_rcp_f32_e32 v88, v86
	v_div_fmas_f32 v81, v81, v87, v82
	v_div_fixup_f32 v82, v81, v80, v18
	v_fma_f32 v80, -v86, v88, 1.0
	v_fmac_f32_e32 v88, v80, v88
	v_div_scale_f32 v80, vcc, v17, v85, v17
	v_mul_f32_e32 v81, v80, v88
	v_fma_f32 v87, -v86, v81, v80
	v_fmac_f32_e32 v81, v87, v88
	v_fma_f32 v80, -v86, v81, v80
	v_div_scale_f32 v86, s[4:5], v84, v84, v16
	v_rcp_f32_e32 v90, v86
	v_div_fmas_f32 v80, v80, v88, v81
	v_div_fixup_f32 v81, v80, v85, v17
	v_mul_f32_e32 v88, 0xbfb8aa3b, v20
	v_fma_f32 v80, -v86, v90, 1.0
	v_fmac_f32_e32 v90, v80, v90
	v_div_scale_f32 v80, vcc, v16, v84, v16
	v_mul_f32_e32 v85, v80, v90
	v_fma_f32 v87, -v86, v85, v80
	v_fmac_f32_e32 v85, v87, v90
	v_fma_f32 v80, -v86, v85, v80
	v_mul_f32_e32 v86, 0xbfb8aa3b, v22
	v_mul_f32_e32 v87, 0xbfb8aa3b, v23
	v_exp_f32_e32 v86, v86
	v_exp_f32_e32 v87, v87
	v_exp_f32_e32 v88, v88
	v_div_fmas_f32 v80, v80, v90, v85
	v_div_fixup_f32 v80, v80, v84, v16
	v_pk_add_f32 v[86:87], v[86:87], 1.0 op_sel_hi:[1,0]
	v_pk_add_f32 v[84:85], v[88:89], 1.0 op_sel_hi:[1,0]
	v_div_scale_f32 v91, s[4:5], v87, v87, v23
	v_rcp_f32_e32 v92, v91
	s_nop 0
	v_fma_f32 v88, -v91, v92, 1.0
	v_fmac_f32_e32 v92, v88, v92
	v_div_scale_f32 v88, vcc, v23, v87, v23
	v_mul_f32_e32 v89, v88, v92
	v_fma_f32 v90, -v91, v89, v88
	v_fmac_f32_e32 v89, v90, v92
	v_div_scale_f32 v90, s[4:5], v86, v86, v22
	v_fma_f32 v88, -v91, v89, v88
	v_rcp_f32_e32 v91, v90
	v_div_fmas_f32 v88, v88, v92, v89
	v_div_fixup_f32 v87, v88, v87, v23
	v_fma_f32 v88, -v90, v91, 1.0
	v_fmac_f32_e32 v91, v88, v91
	v_div_scale_f32 v88, vcc, v22, v86, v22
	v_mul_f32_e32 v89, v88, v91
	v_fma_f32 v92, -v90, v89, v88
	v_fmac_f32_e32 v89, v92, v91
	v_fma_f32 v88, -v90, v89, v88
	v_div_scale_f32 v90, s[4:5], v85, v85, v21
	v_rcp_f32_e32 v92, v90
	v_div_fmas_f32 v88, v88, v91, v89
	v_div_fixup_f32 v86, v88, v86, v22
	v_fma_f32 v88, -v90, v92, 1.0
	v_fmac_f32_e32 v92, v88, v92
	v_div_scale_f32 v88, vcc, v21, v85, v21
	v_mul_f32_e32 v89, v88, v92
	v_fma_f32 v91, -v90, v89, v88
	v_fmac_f32_e32 v89, v91, v92
	v_fma_f32 v88, -v90, v89, v88
	v_div_scale_f32 v90, s[4:5], v84, v84, v20
	v_rcp_f32_e32 v93, v90
	v_div_fmas_f32 v88, v88, v92, v89
	v_div_fixup_f32 v85, v88, v85, v21
	v_mul_f32_e32 v91, 0xbfb8aa3b, v25
	v_fma_f32 v88, -v90, v93, 1.0
	v_fmac_f32_e32 v93, v88, v93
	v_div_scale_f32 v88, vcc, v20, v84, v20
	v_mul_f32_e32 v92, v88, v93
	v_fma_f32 v89, -v90, v92, v88
	v_fmac_f32_e32 v92, v89, v93
	v_fma_f32 v94, -v90, v92, v88
	v_mul_f32_e32 v88, 0xbfb8aa3b, v26
	v_mul_f32_e32 v89, 0xbfb8aa3b, v27
	v_exp_f32_e32 v88, v88
	v_exp_f32_e32 v89, v89
	v_mul_f32_e32 v90, 0xbfb8aa3b, v24
	v_exp_f32_e32 v90, v90
	v_exp_f32_e32 v91, v91
	v_pk_add_f32 v[88:89], v[88:89], 1.0 op_sel_hi:[1,0]
	v_div_fmas_f32 v92, v94, v93, v92
	v_div_scale_f32 v95, s[4:5], v89, v89, v27
	v_rcp_f32_e32 v96, v95
	v_div_fixup_f32 v84, v92, v84, v20
	v_pk_add_f32 v[92:93], v[90:91], 1.0 op_sel_hi:[1,0]
	v_fma_f32 v90, -v95, v96, 1.0
	v_fmac_f32_e32 v96, v90, v96
	v_div_scale_f32 v90, vcc, v27, v89, v27
	v_mul_f32_e32 v91, v90, v96
	v_fma_f32 v94, -v95, v91, v90
	v_fmac_f32_e32 v91, v94, v96
	v_div_scale_f32 v94, s[4:5], v88, v88, v26
	v_fma_f32 v90, -v95, v91, v90
	v_rcp_f32_e32 v95, v94
	v_div_fmas_f32 v90, v90, v96, v91
	v_div_fixup_f32 v91, v90, v89, v27
	v_fma_f32 v89, -v94, v95, 1.0
	v_fmac_f32_e32 v95, v89, v95
	v_div_scale_f32 v89, vcc, v26, v88, v26
	v_mul_f32_e32 v90, v89, v95
	v_fma_f32 v96, -v94, v90, v89
	v_fmac_f32_e32 v90, v96, v95
	v_fma_f32 v89, -v94, v90, v89
	v_div_scale_f32 v94, s[4:5], v93, v93, v25
	v_rcp_f32_e32 v96, v94
	v_div_fmas_f32 v89, v89, v95, v90
	v_div_fixup_f32 v90, v89, v88, v26
	v_fma_f32 v88, -v94, v96, 1.0
	v_fmac_f32_e32 v96, v88, v96
	v_div_scale_f32 v88, vcc, v25, v93, v25
	v_mul_f32_e32 v89, v88, v96
	v_fma_f32 v95, -v94, v89, v88
	v_fmac_f32_e32 v89, v95, v96
	v_fma_f32 v88, -v94, v89, v88
	v_div_scale_f32 v94, s[4:5], v92, v92, v24
	v_rcp_f32_e32 v98, v94
	v_div_fmas_f32 v88, v88, v96, v89
	v_div_fixup_f32 v89, v88, v93, v25
	v_mul_f32_e32 v96, 0xbfb8aa3b, v28
	v_fma_f32 v88, -v94, v98, 1.0
	v_fmac_f32_e32 v98, v88, v98
	v_div_scale_f32 v88, vcc, v24, v92, v24
	v_mul_f32_e32 v93, v88, v98
	v_fma_f32 v95, -v94, v93, v88
	v_fmac_f32_e32 v93, v95, v98
	v_fma_f32 v88, -v94, v93, v88
	v_mul_f32_e32 v94, 0xbfb8aa3b, v30
	v_mul_f32_e32 v95, 0xbfb8aa3b, v31
	v_exp_f32_e32 v94, v94
	v_exp_f32_e32 v95, v95
	v_exp_f32_e32 v96, v96
	v_div_fmas_f32 v88, v88, v98, v93
	v_div_fixup_f32 v88, v88, v92, v24
	v_pk_add_f32 v[94:95], v[94:95], 1.0 op_sel_hi:[1,0]
	v_pk_add_f32 v[92:93], v[96:97], 1.0 op_sel_hi:[1,0]
	v_div_scale_f32 v99, s[4:5], v95, v95, v31
	v_rcp_f32_e32 v100, v99
	s_nop 0
	v_fma_f32 v96, -v99, v100, 1.0
	v_fmac_f32_e32 v100, v96, v100
	v_div_scale_f32 v96, vcc, v31, v95, v31
	v_mul_f32_e32 v97, v96, v100
	v_fma_f32 v98, -v99, v97, v96
	v_fmac_f32_e32 v97, v98, v100
	v_div_scale_f32 v98, s[4:5], v94, v94, v30
	v_fma_f32 v96, -v99, v97, v96
	v_rcp_f32_e32 v99, v98
	v_div_fmas_f32 v96, v96, v100, v97
	v_div_fixup_f32 v95, v96, v95, v31
	v_fma_f32 v96, -v98, v99, 1.0
	v_fmac_f32_e32 v99, v96, v99
	v_div_scale_f32 v96, vcc, v30, v94, v30
	v_mul_f32_e32 v97, v96, v99
	v_fma_f32 v100, -v98, v97, v96
	v_fmac_f32_e32 v97, v100, v99
	v_fma_f32 v96, -v98, v97, v96
	v_div_scale_f32 v98, s[4:5], v93, v93, v29
	v_rcp_f32_e32 v100, v98
	v_div_fmas_f32 v96, v96, v99, v97
	v_div_fixup_f32 v94, v96, v94, v30
	v_fma_f32 v96, -v98, v100, 1.0
	v_fmac_f32_e32 v100, v96, v100
	v_div_scale_f32 v96, vcc, v29, v93, v29
	v_mul_f32_e32 v97, v96, v100
	v_fma_f32 v99, -v98, v97, v96
	v_fmac_f32_e32 v97, v99, v100
	v_fma_f32 v96, -v98, v97, v96
	v_div_scale_f32 v98, s[4:5], v92, v92, v28
	v_rcp_f32_e32 v101, v98
	v_div_fmas_f32 v96, v96, v100, v97
	v_div_fixup_f32 v93, v96, v93, v29
	v_mul_f32_e32 v99, 0xbfb8aa3b, v33
	v_fma_f32 v96, -v98, v101, 1.0
	v_fmac_f32_e32 v101, v96, v101
	v_div_scale_f32 v96, vcc, v28, v92, v28
	v_mul_f32_e32 v100, v96, v101
	v_fma_f32 v97, -v98, v100, v96
	v_fmac_f32_e32 v100, v97, v101
	v_fma_f32 v102, -v98, v100, v96
	v_mul_f32_e32 v96, 0xbfb8aa3b, v34
	v_mul_f32_e32 v97, 0xbfb8aa3b, v35
	v_exp_f32_e32 v96, v96
	v_exp_f32_e32 v97, v97
	v_mul_f32_e32 v98, 0xbfb8aa3b, v32
	v_exp_f32_e32 v98, v98
	v_exp_f32_e32 v99, v99
	v_pk_add_f32 v[96:97], v[96:97], 1.0 op_sel_hi:[1,0]
	v_div_fmas_f32 v100, v102, v101, v100
	v_div_scale_f32 v103, s[4:5], v97, v97, v35
	v_rcp_f32_e32 v104, v103
	v_div_fixup_f32 v92, v100, v92, v28
	v_pk_add_f32 v[100:101], v[98:99], 1.0 op_sel_hi:[1,0]
	v_fma_f32 v98, -v103, v104, 1.0
	v_fmac_f32_e32 v104, v98, v104
	v_div_scale_f32 v98, vcc, v35, v97, v35
	v_mul_f32_e32 v99, v98, v104
	v_fma_f32 v102, -v103, v99, v98
	v_fmac_f32_e32 v99, v102, v104
	v_div_scale_f32 v102, s[4:5], v96, v96, v34
	v_fma_f32 v98, -v103, v99, v98
	v_rcp_f32_e32 v103, v102
	v_div_fmas_f32 v98, v98, v104, v99
	v_div_fixup_f32 v99, v98, v97, v35
	v_fma_f32 v97, -v102, v103, 1.0
	v_fmac_f32_e32 v103, v97, v103
	v_div_scale_f32 v97, vcc, v34, v96, v34
	v_mul_f32_e32 v98, v97, v103
	v_fma_f32 v104, -v102, v98, v97
	v_fmac_f32_e32 v98, v104, v103
	v_fma_f32 v97, -v102, v98, v97
	v_div_scale_f32 v102, s[4:5], v101, v101, v33
	v_rcp_f32_e32 v104, v102
	v_div_fmas_f32 v97, v97, v103, v98
	v_div_fixup_f32 v98, v97, v96, v34
	v_fma_f32 v96, -v102, v104, 1.0
	v_fmac_f32_e32 v104, v96, v104
	v_div_scale_f32 v96, vcc, v33, v101, v33
	v_mul_f32_e32 v97, v96, v104
	v_fma_f32 v103, -v102, v97, v96
	v_fmac_f32_e32 v97, v103, v104
	v_fma_f32 v96, -v102, v97, v96
	v_div_scale_f32 v102, s[4:5], v100, v100, v32
	v_rcp_f32_e32 v106, v102
	v_div_fmas_f32 v96, v96, v104, v97
	v_div_fixup_f32 v97, v96, v101, v33
	v_mul_f32_e32 v104, 0xbfb8aa3b, v36
	v_fma_f32 v96, -v102, v106, 1.0
	v_fmac_f32_e32 v106, v96, v106
	v_div_scale_f32 v96, vcc, v32, v100, v32
	v_mul_f32_e32 v101, v96, v106
	v_fma_f32 v103, -v102, v101, v96
	v_fmac_f32_e32 v101, v103, v106
	v_fma_f32 v96, -v102, v101, v96
	v_mul_f32_e32 v102, 0xbfb8aa3b, v38
	v_mul_f32_e32 v103, 0xbfb8aa3b, v39
	v_exp_f32_e32 v102, v102
	v_exp_f32_e32 v103, v103
	v_exp_f32_e32 v104, v104
	v_div_fmas_f32 v96, v96, v106, v101
	v_div_fixup_f32 v96, v96, v100, v32
	v_pk_add_f32 v[102:103], v[102:103], 1.0 op_sel_hi:[1,0]
	v_pk_add_f32 v[100:101], v[104:105], 1.0 op_sel_hi:[1,0]
	v_div_scale_f32 v107, s[4:5], v103, v103, v39
	v_rcp_f32_e32 v108, v107
	s_nop 0
	v_fma_f32 v104, -v107, v108, 1.0
	v_fmac_f32_e32 v108, v104, v108
	v_div_scale_f32 v104, vcc, v39, v103, v39
	v_mul_f32_e32 v105, v104, v108
	v_fma_f32 v106, -v107, v105, v104
	v_fmac_f32_e32 v105, v106, v108
	v_div_scale_f32 v106, s[4:5], v102, v102, v38
	v_fma_f32 v104, -v107, v105, v104
	v_rcp_f32_e32 v107, v106
	v_div_fmas_f32 v104, v104, v108, v105
	v_div_fixup_f32 v103, v104, v103, v39
	v_fma_f32 v104, -v106, v107, 1.0
	v_fmac_f32_e32 v107, v104, v107
	v_div_scale_f32 v104, vcc, v38, v102, v38
	v_mul_f32_e32 v105, v104, v107
	v_fma_f32 v108, -v106, v105, v104
	v_fmac_f32_e32 v105, v108, v107
	v_fma_f32 v104, -v106, v105, v104
	v_div_scale_f32 v106, s[4:5], v101, v101, v37
	v_rcp_f32_e32 v108, v106
	v_div_fmas_f32 v104, v104, v107, v105
	v_div_fixup_f32 v102, v104, v102, v38
	v_fma_f32 v104, -v106, v108, 1.0
	v_fmac_f32_e32 v108, v104, v108
	v_div_scale_f32 v104, vcc, v37, v101, v37
	v_mul_f32_e32 v105, v104, v108
	v_fma_f32 v107, -v106, v105, v104
	v_fmac_f32_e32 v105, v107, v108
	v_fma_f32 v104, -v106, v105, v104
	v_div_scale_f32 v106, s[4:5], v100, v100, v36
	v_rcp_f32_e32 v109, v106
	v_div_fmas_f32 v104, v104, v108, v105
	v_div_fixup_f32 v101, v104, v101, v37
	v_mul_f32_e32 v107, 0xbfb8aa3b, v41
	v_fma_f32 v104, -v106, v109, 1.0
	v_fmac_f32_e32 v109, v104, v109
	v_div_scale_f32 v104, vcc, v36, v100, v36
	v_mul_f32_e32 v108, v104, v109
	v_fma_f32 v105, -v106, v108, v104
	v_fmac_f32_e32 v108, v105, v109
	v_fma_f32 v110, -v106, v108, v104
	v_mul_f32_e32 v104, 0xbfb8aa3b, v42
	v_mul_f32_e32 v105, 0xbfb8aa3b, v43
	v_exp_f32_e32 v104, v104
	v_exp_f32_e32 v105, v105
	v_mul_f32_e32 v106, 0xbfb8aa3b, v40
	v_exp_f32_e32 v106, v106
	v_exp_f32_e32 v107, v107
	v_pk_add_f32 v[104:105], v[104:105], 1.0 op_sel_hi:[1,0]
	v_div_fmas_f32 v108, v110, v109, v108
	v_div_scale_f32 v111, s[4:5], v105, v105, v43
	v_rcp_f32_e32 v112, v111
	v_div_fixup_f32 v100, v108, v100, v36
	v_pk_add_f32 v[108:109], v[106:107], 1.0 op_sel_hi:[1,0]
	v_fma_f32 v106, -v111, v112, 1.0
	v_fmac_f32_e32 v112, v106, v112
	v_div_scale_f32 v106, vcc, v43, v105, v43
	v_mul_f32_e32 v107, v106, v112
	v_fma_f32 v110, -v111, v107, v106
	v_fmac_f32_e32 v107, v110, v112
	v_div_scale_f32 v110, s[4:5], v104, v104, v42
	v_fma_f32 v106, -v111, v107, v106
	v_rcp_f32_e32 v111, v110
	v_div_fmas_f32 v106, v106, v112, v107
	v_div_fixup_f32 v107, v106, v105, v43
	v_fma_f32 v105, -v110, v111, 1.0
	v_fmac_f32_e32 v111, v105, v111
	v_div_scale_f32 v105, vcc, v42, v104, v42
	v_mul_f32_e32 v106, v105, v111
	v_fma_f32 v112, -v110, v106, v105
	v_fmac_f32_e32 v106, v112, v111
	v_fma_f32 v105, -v110, v106, v105
	v_div_scale_f32 v110, s[4:5], v109, v109, v41
	v_rcp_f32_e32 v112, v110
	v_div_fmas_f32 v105, v105, v111, v106
	v_div_fixup_f32 v106, v105, v104, v42
	v_fma_f32 v104, -v110, v112, 1.0
	v_fmac_f32_e32 v112, v104, v112
	v_div_scale_f32 v104, vcc, v41, v109, v41
	v_mul_f32_e32 v105, v104, v112
	v_fma_f32 v111, -v110, v105, v104
	v_fmac_f32_e32 v105, v111, v112
	v_fma_f32 v104, -v110, v105, v104
	v_div_scale_f32 v110, s[4:5], v108, v108, v40
	v_rcp_f32_e32 v114, v110
	v_div_fmas_f32 v104, v104, v112, v105
	v_div_fixup_f32 v105, v104, v109, v41
	v_mul_f32_e32 v112, 0xbfb8aa3b, v44
	v_fma_f32 v104, -v110, v114, 1.0
	v_fmac_f32_e32 v114, v104, v114
	v_div_scale_f32 v104, vcc, v40, v108, v40
	v_mul_f32_e32 v109, v104, v114
	v_fma_f32 v111, -v110, v109, v104
	v_fmac_f32_e32 v109, v111, v114
	v_fma_f32 v104, -v110, v109, v104
	v_mul_f32_e32 v110, 0xbfb8aa3b, v46
	v_mul_f32_e32 v111, 0xbfb8aa3b, v47
	v_exp_f32_e32 v110, v110
	v_exp_f32_e32 v111, v111
	v_exp_f32_e32 v112, v112
	v_div_fmas_f32 v104, v104, v114, v109
	v_div_fixup_f32 v104, v104, v108, v40
	v_pk_add_f32 v[110:111], v[110:111], 1.0 op_sel_hi:[1,0]
	v_pk_add_f32 v[108:109], v[112:113], 1.0 op_sel_hi:[1,0]
	v_div_scale_f32 v115, s[4:5], v111, v111, v47
	v_rcp_f32_e32 v116, v115
	s_nop 0
	v_fma_f32 v112, -v115, v116, 1.0
	v_fmac_f32_e32 v116, v112, v116
	v_div_scale_f32 v112, vcc, v47, v111, v47
	v_mul_f32_e32 v113, v112, v116
	v_fma_f32 v114, -v115, v113, v112
	v_fmac_f32_e32 v113, v114, v116
	v_div_scale_f32 v114, s[4:5], v110, v110, v46
	v_fma_f32 v112, -v115, v113, v112
	v_rcp_f32_e32 v115, v114
	v_div_fmas_f32 v112, v112, v116, v113
	v_div_fixup_f32 v111, v112, v111, v47
	v_fma_f32 v112, -v114, v115, 1.0
	v_fmac_f32_e32 v115, v112, v115
	v_div_scale_f32 v112, vcc, v46, v110, v46
	v_mul_f32_e32 v113, v112, v115
	v_fma_f32 v116, -v114, v113, v112
	v_fmac_f32_e32 v113, v116, v115
	v_fma_f32 v112, -v114, v113, v112
	v_div_scale_f32 v114, s[4:5], v109, v109, v45
	v_rcp_f32_e32 v116, v114
	v_div_fmas_f32 v112, v112, v115, v113
	v_div_fixup_f32 v110, v112, v110, v46
	v_fma_f32 v112, -v114, v116, 1.0
	v_fmac_f32_e32 v116, v112, v116
	v_div_scale_f32 v112, vcc, v45, v109, v45
	v_mul_f32_e32 v113, v112, v116
	v_fma_f32 v115, -v114, v113, v112
	v_fmac_f32_e32 v113, v115, v116
	v_fma_f32 v112, -v114, v113, v112
	v_div_scale_f32 v114, s[4:5], v108, v108, v44
	v_rcp_f32_e32 v117, v114
	v_div_fmas_f32 v112, v112, v116, v113
	v_div_fixup_f32 v109, v112, v109, v45
	v_mul_f32_e32 v115, 0xbfb8aa3b, v49
	v_fma_f32 v112, -v114, v117, 1.0
	v_fmac_f32_e32 v117, v112, v117
	v_div_scale_f32 v112, vcc, v44, v108, v44
	v_mul_f32_e32 v116, v112, v117
	v_fma_f32 v113, -v114, v116, v112
	v_fmac_f32_e32 v116, v113, v117
	v_fma_f32 v118, -v114, v116, v112
	v_mul_f32_e32 v112, 0xbfb8aa3b, v50
	v_mul_f32_e32 v113, 0xbfb8aa3b, v51
	v_exp_f32_e32 v112, v112
	v_exp_f32_e32 v113, v113
	v_mul_f32_e32 v114, 0xbfb8aa3b, v48
	v_exp_f32_e32 v114, v114
	v_exp_f32_e32 v115, v115
	v_pk_add_f32 v[112:113], v[112:113], 1.0 op_sel_hi:[1,0]
	v_div_fmas_f32 v116, v118, v117, v116
	v_div_scale_f32 v119, s[4:5], v113, v113, v51
	v_rcp_f32_e32 v120, v119
	v_div_fixup_f32 v108, v116, v108, v44
	v_pk_add_f32 v[116:117], v[114:115], 1.0 op_sel_hi:[1,0]
	v_fma_f32 v114, -v119, v120, 1.0
	v_fmac_f32_e32 v120, v114, v120
	v_div_scale_f32 v114, vcc, v51, v113, v51
	v_mul_f32_e32 v115, v114, v120
	v_fma_f32 v118, -v119, v115, v114
	v_fmac_f32_e32 v115, v118, v120
	v_div_scale_f32 v118, s[4:5], v112, v112, v50
	v_fma_f32 v114, -v119, v115, v114
	v_rcp_f32_e32 v119, v118
	v_div_fmas_f32 v114, v114, v120, v115
	v_div_fixup_f32 v115, v114, v113, v51
	v_fma_f32 v113, -v118, v119, 1.0
	v_fmac_f32_e32 v119, v113, v119
	v_div_scale_f32 v113, vcc, v50, v112, v50
	v_mul_f32_e32 v114, v113, v119
	v_fma_f32 v120, -v118, v114, v113
	v_fmac_f32_e32 v114, v120, v119
	v_fma_f32 v113, -v118, v114, v113
	v_div_scale_f32 v118, s[4:5], v117, v117, v49
	v_rcp_f32_e32 v120, v118
	v_div_fmas_f32 v113, v113, v119, v114
	v_div_fixup_f32 v114, v113, v112, v50
	v_fma_f32 v112, -v118, v120, 1.0
	v_fmac_f32_e32 v120, v112, v120
	v_div_scale_f32 v112, vcc, v49, v117, v49
	v_mul_f32_e32 v113, v112, v120
	v_fma_f32 v119, -v118, v113, v112
	v_fmac_f32_e32 v113, v119, v120
	v_fma_f32 v112, -v118, v113, v112
	v_div_scale_f32 v118, s[4:5], v116, v116, v48
	v_rcp_f32_e32 v122, v118
	v_div_fmas_f32 v112, v112, v120, v113
	v_div_fixup_f32 v113, v112, v117, v49
	v_mul_f32_e32 v120, 0xbfb8aa3b, v52
	v_fma_f32 v112, -v118, v122, 1.0
	v_fmac_f32_e32 v122, v112, v122
	v_div_scale_f32 v112, vcc, v48, v116, v48
	v_mul_f32_e32 v117, v112, v122
	v_fma_f32 v119, -v118, v117, v112
	v_fmac_f32_e32 v117, v119, v122
	v_fma_f32 v112, -v118, v117, v112
	v_mul_f32_e32 v118, 0xbfb8aa3b, v54
	v_mul_f32_e32 v119, 0xbfb8aa3b, v55
	v_exp_f32_e32 v118, v118
	v_exp_f32_e32 v119, v119
	v_exp_f32_e32 v120, v120
	v_div_fmas_f32 v112, v112, v122, v117
	v_div_fixup_f32 v112, v112, v116, v48
	v_pk_add_f32 v[118:119], v[118:119], 1.0 op_sel_hi:[1,0]
	v_pk_add_f32 v[116:117], v[120:121], 1.0 op_sel_hi:[1,0]
	v_div_scale_f32 v123, s[4:5], v119, v119, v55
	v_rcp_f32_e32 v124, v123
	s_nop 0
	v_fma_f32 v120, -v123, v124, 1.0
	v_fmac_f32_e32 v124, v120, v124
	v_div_scale_f32 v120, vcc, v55, v119, v55
	v_mul_f32_e32 v121, v120, v124
	v_fma_f32 v122, -v123, v121, v120
	v_fmac_f32_e32 v121, v122, v124
	v_div_scale_f32 v122, s[4:5], v118, v118, v54
	v_fma_f32 v120, -v123, v121, v120
	v_rcp_f32_e32 v123, v122
	v_div_fmas_f32 v120, v120, v124, v121
	v_div_fixup_f32 v119, v120, v119, v55
	v_fma_f32 v120, -v122, v123, 1.0
	v_fmac_f32_e32 v123, v120, v123
	v_div_scale_f32 v120, vcc, v54, v118, v54
	v_mul_f32_e32 v121, v120, v123
	v_fma_f32 v124, -v122, v121, v120
	v_fmac_f32_e32 v121, v124, v123
	v_fma_f32 v120, -v122, v121, v120
	v_div_scale_f32 v122, s[4:5], v117, v117, v53
	v_rcp_f32_e32 v124, v122
	v_div_fmas_f32 v120, v120, v123, v121
	v_div_fixup_f32 v118, v120, v118, v54
	v_fma_f32 v120, -v122, v124, 1.0
	v_fmac_f32_e32 v124, v120, v124
	v_div_scale_f32 v120, vcc, v53, v117, v53
	v_mul_f32_e32 v121, v120, v124
	v_fma_f32 v123, -v122, v121, v120
	v_fmac_f32_e32 v121, v123, v124
	v_fma_f32 v120, -v122, v121, v120
	v_div_scale_f32 v122, s[4:5], v116, v116, v52
	v_rcp_f32_e32 v125, v122
	v_div_fmas_f32 v120, v120, v124, v121
	v_div_fixup_f32 v117, v120, v117, v53
	v_mul_f32_e32 v123, 0xbfb8aa3b, v57
	v_fma_f32 v120, -v122, v125, 1.0
	v_fmac_f32_e32 v125, v120, v125
	v_div_scale_f32 v120, vcc, v52, v116, v52
	v_mul_f32_e32 v124, v120, v125
	v_fma_f32 v121, -v122, v124, v120
	v_fmac_f32_e32 v124, v121, v125
	v_fma_f32 v126, -v122, v124, v120
	v_mul_f32_e32 v120, 0xbfb8aa3b, v58
	v_mul_f32_e32 v121, 0xbfb8aa3b, v59
	v_exp_f32_e32 v120, v120
	v_exp_f32_e32 v121, v121
	v_mul_f32_e32 v122, 0xbfb8aa3b, v56
	v_exp_f32_e32 v122, v122
	v_exp_f32_e32 v123, v123
	v_pk_add_f32 v[120:121], v[120:121], 1.0 op_sel_hi:[1,0]
	v_div_fmas_f32 v124, v126, v125, v124
	v_div_scale_f32 v127, s[4:5], v121, v121, v59
	v_rcp_f32_e32 v142, v127
	v_div_fixup_f32 v116, v124, v116, v52
	v_pk_add_f32 v[124:125], v[122:123], 1.0 op_sel_hi:[1,0]
	v_fma_f32 v122, -v127, v142, 1.0
	v_fmac_f32_e32 v142, v122, v142
	v_div_scale_f32 v122, vcc, v59, v121, v59
	v_mul_f32_e32 v123, v122, v142
	v_fma_f32 v126, -v127, v123, v122
	v_fmac_f32_e32 v123, v126, v142
	v_div_scale_f32 v126, s[4:5], v120, v120, v58
	v_fma_f32 v122, -v127, v123, v122
	v_rcp_f32_e32 v127, v126
	v_div_fmas_f32 v122, v122, v142, v123
	v_div_fixup_f32 v123, v122, v121, v59
	v_fma_f32 v121, -v126, v127, 1.0
	v_fmac_f32_e32 v127, v121, v127
	v_div_scale_f32 v121, vcc, v58, v120, v58
	v_mul_f32_e32 v122, v121, v127
	v_fma_f32 v142, -v126, v122, v121
	v_fmac_f32_e32 v122, v142, v127
	v_fma_f32 v121, -v126, v122, v121
	v_div_scale_f32 v126, s[4:5], v125, v125, v57
	v_rcp_f32_e32 v142, v126
	v_div_fmas_f32 v121, v121, v127, v122
	v_div_fixup_f32 v122, v121, v120, v58
	v_fma_f32 v120, -v126, v142, 1.0
	v_fmac_f32_e32 v142, v120, v142
	v_div_scale_f32 v120, vcc, v57, v125, v57
	v_mul_f32_e32 v121, v120, v142
	v_fma_f32 v127, -v126, v121, v120
	v_fmac_f32_e32 v121, v127, v142
	v_fma_f32 v120, -v126, v121, v120
	v_div_scale_f32 v126, s[4:5], v124, v124, v56
	v_rcp_f32_e32 v202, v126
	v_div_fmas_f32 v120, v120, v142, v121
	v_div_fixup_f32 v121, v120, v125, v57
	v_mul_f32_e32 v142, 0xbfb8aa3b, v60
	v_fma_f32 v120, -v126, v202, 1.0
	v_fmac_f32_e32 v202, v120, v202
	v_div_scale_f32 v120, vcc, v56, v124, v56
	v_mul_f32_e32 v125, v120, v202
	v_fma_f32 v127, -v126, v125, v120
	v_fmac_f32_e32 v125, v127, v202
	v_fma_f32 v120, -v126, v125, v120
	v_mul_f32_e32 v126, 0xbfb8aa3b, v62
	v_mul_f32_e32 v127, 0xbfb8aa3b, v63
	v_exp_f32_e32 v126, v126
	v_exp_f32_e32 v127, v127
	v_exp_f32_e32 v200, v142
	v_mul_f32_e32 v142, 0xbfb8aa3b, v61
	v_exp_f32_e32 v201, v142
	v_pk_add_f32 v[126:127], v[126:127], 1.0 op_sel_hi:[1,0]
	v_div_fmas_f32 v120, v120, v202, v125
	v_div_scale_f32 v142, s[4:5], v127, v127, v63
	v_rcp_f32_e32 v203, v142
	v_div_fixup_f32 v120, v120, v124, v56
	v_pk_add_f32 v[124:125], v[200:201], 1.0 op_sel_hi:[1,0]
	v_fma_f32 v200, -v142, v203, 1.0
	v_fmac_f32_e32 v203, v200, v203
	v_div_scale_f32 v200, vcc, v63, v127, v63
	v_mul_f32_e32 v201, v200, v203
	v_fma_f32 v202, -v142, v201, v200
	v_fmac_f32_e32 v201, v202, v203
	v_fma_f32 v142, -v142, v201, v200
	v_div_scale_f32 v200, s[4:5], v126, v126, v62
	v_rcp_f32_e32 v202, v200
	v_div_fmas_f32 v142, v142, v203, v201
	v_div_fixup_f32 v127, v142, v127, v63
	v_fma_f32 v142, -v200, v202, 1.0
	v_fmac_f32_e32 v202, v142, v202
	v_div_scale_f32 v142, vcc, v62, v126, v62
	v_mul_f32_e32 v201, v142, v202
	v_fma_f32 v203, -v200, v201, v142
	v_fmac_f32_e32 v201, v203, v202
	v_fma_f32 v142, -v200, v201, v142
	v_div_scale_f32 v200, s[4:5], v125, v125, v61
	v_rcp_f32_e32 v203, v200
	v_div_fmas_f32 v142, v142, v202, v201
	v_div_fixup_f32 v126, v142, v126, v62
	v_fma_f32 v142, -v200, v203, 1.0
	v_fmac_f32_e32 v203, v142, v203
	v_div_scale_f32 v142, vcc, v61, v125, v61
	v_mul_f32_e32 v201, v142, v203
	v_fma_f32 v202, -v200, v201, v142
	v_fmac_f32_e32 v201, v202, v203
	v_fma_f32 v142, -v200, v201, v142
	v_div_scale_f32 v200, s[4:5], v124, v124, v60
	v_rcp_f32_e32 v202, v200
	v_div_fmas_f32 v142, v142, v203, v201
	v_div_fixup_f32 v125, v142, v125, v61
	s_lshl_b64 s[4:5], s[66:67], 19
	v_fma_f32 v142, -v200, v202, 1.0
	v_fmac_f32_e32 v202, v142, v202
	v_div_scale_f32 v142, vcc, v60, v124, v60
	s_add_u32 s4, s36, s4
	v_mul_f32_e32 v201, v142, v202
	s_addc_u32 s5, s37, s5
	s_lshl_b32 s34, s0, 7
	v_fma_f32 v203, -v200, v201, v142
	s_lshl_b64 s[0:1], s[34:35], 1
	v_fmac_f32_e32 v201, v203, v202
	s_add_u32 s0, s4, s0
	v_fma_f32 v142, -v200, v201, v142
	s_addc_u32 s1, s5, s1
	v_div_fmas_f32 v142, v142, v202, v201
	s_add_u32 s4, s0, 0xffffd800
	v_div_fixup_f32 v124, v142, v124, v60
	s_addc_u32 s5, s1, -1
